# peeled first K-loop trip in all 6 GEMM phases (first-touch MFMAs use SrcC=0), removes 128 accumulator-zeroing v_mov per unit per wave
# speedup vs baseline: 1.0224x; 1.0161x over previous
.LBB0_140:
	s_ashr_i32 s37, s36, 31
	s_lshl_b64 s[42:43], s[36:37], 19
	s_add_u32 s42, s62, s42
	s_addc_u32 s43, s63, s43
	s_and_b64 s[44:45], s[0:1], exec
	s_cselect_b32 s37, s43, s49
	s_cselect_b32 s77, s42, s48
	s_ashr_i32 s39, s38, 31
	s_lshl_b64 s[44:45], s[38:39], 19
	s_add_u32 s44, s54, s44
	s_addc_u32 s45, s55, s45
	s_and_b64 s[52:53], s[0:1], exec
	s_cselect_b32 s39, s45, s51
	s_cselect_b32 s78, s44, s50
	s_add_u32 s48, s48, 0x40080
	s_addc_u32 s49, s49, 0
	s_add_u32 s79, s50, 0x100
	s_addc_u32 s80, s51, 0
	s_mov_b32 s81, -2
	ds_read_b128 v[150:153], v147
	ds_read_b128 v[154:157], v147 offset:1024
	ds_read_b128 v[158:161], v147 offset:2048
	ds_read_b128 v[162:165], v147 offset:3072
	ds_read_b128 v[166:169], v148
	ds_read_b128 v[170:173], v148 offset:1024
	ds_read_b128 v[174:177], v148 offset:2048
	ds_read_b128 v[178:181], v148 offset:3072
	s_add_u32 s50, s48, 0xfffc0080
	s_addc_u32 s51, s49, -1
	s_cmp_eq_u32 s81, 12
	s_cselect_b32 s53, s37, s51
	s_cselect_b32 s52, s77, s50
	s_cselect_b32 s51, s39, s80
	s_cselect_b32 s50, s78, s79
	v_lshl_add_u64 v[214:215], s[48:49], 0, v[136:137]
	s_add_i32 m0, s47, 0xc000
	ds_read_b128 v[182:185], v149
	ds_read_b128 v[186:189], v149 offset:1024
	ds_read_b128 v[190:193], v149 offset:2048
	ds_read_b128 v[194:197], v149 offset:3072
	ds_read_b128 v[198:201], v149 offset:4096
	ds_read_b128 v[202:205], v149 offset:5120
	ds_read_b128 v[206:209], v149 offset:6144
	ds_read_b128 v[210:213], v149 offset:7168
	global_load_lds_dwordx4 v[214:215], off
	v_lshl_add_u64 v[214:215], s[48:49], 0, v[138:139]
	s_add_i32 m0, s47, 0xe000
	s_nop 0
	global_load_lds_dwordx4 v[214:215], off
	s_waitcnt vmcnt(8)
	s_waitcnt lgkmcnt(0)
	s_barrier
	s_setprio 1
	s_waitcnt lgkmcnt(0)
	v_mfma_f32_16x16x32_bf16 v[124:127], v[150:153], v[182:185], 0
	v_mfma_f32_16x16x32_bf16 v[116:119], v[158:161], v[182:185], 0
	v_mfma_f32_16x16x32_bf16 v[108:111], v[150:153], v[190:193], 0
	v_mfma_f32_16x16x32_bf16 v[100:103], v[158:161], v[190:193], 0
	v_mfma_f32_16x16x32_bf16 v[92:95], v[150:153], v[198:201], 0
	v_mfma_f32_16x16x32_bf16 v[84:87], v[158:161], v[198:201], 0
	v_mfma_f32_16x16x32_bf16 v[76:79], v[150:153], v[206:209], 0
	v_mfma_f32_16x16x32_bf16 v[68:71], v[158:161], v[206:209], 0
	v_mfma_f32_16x16x32_bf16 v[124:127], v[154:157], v[186:189], v[124:127]
	v_mfma_f32_16x16x32_bf16 v[116:119], v[162:165], v[186:189], v[116:119]
	v_mfma_f32_16x16x32_bf16 v[108:111], v[154:157], v[194:197], v[108:111]
	v_mfma_f32_16x16x32_bf16 v[100:103], v[162:165], v[194:197], v[100:103]
	v_mfma_f32_16x16x32_bf16 v[92:95], v[154:157], v[202:205], v[92:95]
	v_mfma_f32_16x16x32_bf16 v[84:87], v[162:165], v[202:205], v[84:87]
	v_mfma_f32_16x16x32_bf16 v[76:79], v[154:157], v[210:213], v[76:79]
	v_mfma_f32_16x16x32_bf16 v[68:71], v[162:165], v[210:213], v[68:71]
	s_setprio 0
	s_setprio 1
	v_mfma_f32_16x16x32_bf16 v[120:123], v[166:169], v[182:185], 0
	v_mfma_f32_16x16x32_bf16 v[112:115], v[174:177], v[182:185], 0
	v_mfma_f32_16x16x32_bf16 v[104:107], v[166:169], v[190:193], 0
	v_mfma_f32_16x16x32_bf16 v[96:99], v[174:177], v[190:193], 0
	v_mfma_f32_16x16x32_bf16 v[88:91], v[166:169], v[198:201], 0
	v_mfma_f32_16x16x32_bf16 v[80:83], v[174:177], v[198:201], 0
	v_mfma_f32_16x16x32_bf16 v[72:75], v[166:169], v[206:209], 0
	v_mfma_f32_16x16x32_bf16 v[64:67], v[174:177], v[206:209], 0
	v_mfma_f32_16x16x32_bf16 v[120:123], v[170:173], v[186:189], v[120:123]
	v_mfma_f32_16x16x32_bf16 v[112:115], v[178:181], v[186:189], v[112:115]
	v_mfma_f32_16x16x32_bf16 v[104:107], v[170:173], v[194:197], v[104:107]
	v_mfma_f32_16x16x32_bf16 v[96:99], v[178:181], v[194:197], v[96:99]
	v_mfma_f32_16x16x32_bf16 v[88:91], v[170:173], v[202:205], v[88:91]
	v_mfma_f32_16x16x32_bf16 v[80:83], v[178:181], v[202:205], v[80:83]
	v_mfma_f32_16x16x32_bf16 v[72:75], v[170:173], v[210:213], v[72:75]
	v_mfma_f32_16x16x32_bf16 v[64:67], v[178:181], v[210:213], v[64:67]
	s_setprio 0
	s_barrier
	s_add_i32 s82, s73, s56
	v_lshl_add_u64 v[214:215], s[50:51], 0, v[132:133]
	s_mov_b32 m0, s82
	ds_read_b128 v[182:185], v149 offset:16384
	ds_read_b128 v[186:189], v149 offset:17408
	ds_read_b128 v[190:193], v149 offset:18432
	ds_read_b128 v[194:197], v149 offset:19456
	ds_read_b128 v[198:201], v149 offset:20480
	ds_read_b128 v[202:205], v149 offset:21504
	ds_read_b128 v[206:209], v149 offset:22528
	ds_read_b128 v[210:213], v149 offset:23552
	global_load_lds_dwordx4 v[214:215], off
	s_add_i32 m0, s82, 0x2000
	s_add_u32 s88, s50, 0x40000
	v_lshl_add_u64 v[216:217], s[50:51], 0, v[128:129]
	s_addc_u32 s89, s51, 0
	s_add_i32 s82, s74, s56
	global_load_lds_dwordx4 v[216:217], off
	v_lshl_add_u64 v[218:219], s[88:89], 0, v[132:133]
	s_mov_b32 m0, s82
	v_lshl_add_u64 v[220:221], s[52:53], 0, v[130:131]
	global_load_lds_dwordx4 v[218:219], off
	v_lshl_add_u64 v[218:219], s[88:89], 0, v[128:129]
	s_add_i32 m0, s82, 0x2000
	s_nop 0
	global_load_lds_dwordx4 v[218:219], off
	v_lshl_add_u64 v[218:219], s[52:53], 0, v[134:135]
	s_mov_b32 m0, s47
	s_nop 0
	global_load_lds_dwordx4 v[218:219], off
	s_mov_b32 m0, s59
	s_nop 0
	global_load_lds_dwordx4 v[220:221], off
	s_waitcnt vmcnt(8)
	s_waitcnt lgkmcnt(0)
	s_barrier
	s_setprio 1
	s_waitcnt lgkmcnt(0)
	v_mfma_f32_16x16x32_bf16 v[60:63], v[150:153], v[182:185], 0
	v_mfma_f32_16x16x32_bf16 v[52:55], v[158:161], v[182:185], 0
	v_mfma_f32_16x16x32_bf16 v[44:47], v[150:153], v[190:193], 0
	v_mfma_f32_16x16x32_bf16 v[36:39], v[158:161], v[190:193], 0
	v_mfma_f32_16x16x32_bf16 v[28:31], v[150:153], v[198:201], 0
	v_mfma_f32_16x16x32_bf16 v[20:23], v[158:161], v[198:201], 0
	v_mfma_f32_16x16x32_bf16 v[12:15], v[150:153], v[206:209], 0
	v_mfma_f32_16x16x32_bf16 v[4:7], v[158:161], v[206:209], 0
	v_mfma_f32_16x16x32_bf16 v[60:63], v[154:157], v[186:189], v[60:63]
	v_mfma_f32_16x16x32_bf16 v[52:55], v[162:165], v[186:189], v[52:55]
	v_mfma_f32_16x16x32_bf16 v[44:47], v[154:157], v[194:197], v[44:47]
	v_mfma_f32_16x16x32_bf16 v[36:39], v[162:165], v[194:197], v[36:39]
	v_mfma_f32_16x16x32_bf16 v[28:31], v[154:157], v[202:205], v[28:31]
	v_mfma_f32_16x16x32_bf16 v[20:23], v[162:165], v[202:205], v[20:23]
	v_mfma_f32_16x16x32_bf16 v[12:15], v[154:157], v[210:213], v[12:15]
	v_mfma_f32_16x16x32_bf16 v[4:7], v[162:165], v[210:213], v[4:7]
	s_setprio 0
	s_setprio 1
	v_mfma_f32_16x16x32_bf16 v[56:59], v[166:169], v[182:185], 0
	v_mfma_f32_16x16x32_bf16 v[48:51], v[174:177], v[182:185], 0
	v_mfma_f32_16x16x32_bf16 v[40:43], v[166:169], v[190:193], 0
	v_mfma_f32_16x16x32_bf16 v[32:35], v[174:177], v[190:193], 0
	v_mfma_f32_16x16x32_bf16 v[24:27], v[166:169], v[198:201], 0
	v_mfma_f32_16x16x32_bf16 v[16:19], v[174:177], v[198:201], 0
	v_mfma_f32_16x16x32_bf16 v[8:11], v[166:169], v[206:209], 0
	v_mfma_f32_16x16x32_bf16 v[0:3], v[174:177], v[206:209], 0
	v_mfma_f32_16x16x32_bf16 v[56:59], v[170:173], v[186:189], v[56:59]
	v_mfma_f32_16x16x32_bf16 v[48:51], v[178:181], v[186:189], v[48:51]
	v_mfma_f32_16x16x32_bf16 v[40:43], v[170:173], v[194:197], v[40:43]
	v_mfma_f32_16x16x32_bf16 v[32:35], v[178:181], v[194:197], v[32:35]
	v_mfma_f32_16x16x32_bf16 v[24:27], v[170:173], v[202:205], v[24:27]
	v_mfma_f32_16x16x32_bf16 v[16:19], v[178:181], v[202:205], v[16:19]
	v_mfma_f32_16x16x32_bf16 v[8:11], v[170:173], v[210:213], v[8:11]
	v_mfma_f32_16x16x32_bf16 v[0:3], v[178:181], v[210:213], v[0:3]
	s_setprio 0
	s_barrier
	s_add_i32 s82, 0, 0x18000
	s_add_i32 s85, 0, 0x1c000
	v_add_u32_e32 v162, s82, v145
	v_add_u32_e32 v178, s85, v145
	ds_read_b128 v[150:153], v162
	ds_read_b128 v[154:157], v162 offset:1024
	ds_read_b128 v[158:161], v162 offset:2048
	ds_read_b128 v[162:165], v162 offset:3072
	ds_read_b128 v[166:169], v178
	ds_read_b128 v[170:173], v178 offset:1024
	ds_read_b128 v[174:177], v178 offset:2048
	ds_read_b128 v[178:181], v178 offset:3072
	s_add_u32 s52, s52, 0x40000
	s_addc_u32 s53, s53, 0
	s_mov_b32 m0, s66
	v_lshl_add_u64 v[222:223], s[52:53], 0, v[134:135]
	ds_read_b128 v[182:185], v149 offset:32768
	ds_read_b128 v[186:189], v149 offset:33792
	ds_read_b128 v[190:193], v149 offset:34816
	ds_read_b128 v[194:197], v149 offset:35840
	ds_read_b128 v[198:201], v149 offset:36864
	ds_read_b128 v[202:205], v149 offset:37888
	ds_read_b128 v[206:209], v149 offset:38912
	ds_read_b128 v[210:213], v149 offset:39936
	global_load_lds_dwordx4 v[222:223], off
	v_lshl_add_u64 v[222:223], s[52:53], 0, v[130:131]
	s_mov_b32 m0, s67
	s_nop 0
	global_load_lds_dwordx4 v[222:223], off
	s_waitcnt vmcnt(8)
	s_waitcnt lgkmcnt(0)
	s_barrier
	s_setprio 1
	s_waitcnt lgkmcnt(0)
	v_mfma_f32_16x16x32_bf16 v[124:127], v[150:153], v[182:185], v[124:127]
	v_mfma_f32_16x16x32_bf16 v[116:119], v[158:161], v[182:185], v[116:119]
	v_mfma_f32_16x16x32_bf16 v[108:111], v[150:153], v[190:193], v[108:111]
	v_mfma_f32_16x16x32_bf16 v[100:103], v[158:161], v[190:193], v[100:103]
	v_mfma_f32_16x16x32_bf16 v[92:95], v[150:153], v[198:201], v[92:95]
	v_mfma_f32_16x16x32_bf16 v[84:87], v[158:161], v[198:201], v[84:87]
	v_mfma_f32_16x16x32_bf16 v[76:79], v[150:153], v[206:209], v[76:79]
	v_mfma_f32_16x16x32_bf16 v[68:71], v[158:161], v[206:209], v[68:71]
	v_mfma_f32_16x16x32_bf16 v[124:127], v[154:157], v[186:189], v[124:127]
	v_mfma_f32_16x16x32_bf16 v[116:119], v[162:165], v[186:189], v[116:119]
	v_mfma_f32_16x16x32_bf16 v[108:111], v[154:157], v[194:197], v[108:111]
	v_mfma_f32_16x16x32_bf16 v[100:103], v[162:165], v[194:197], v[100:103]
	v_mfma_f32_16x16x32_bf16 v[92:95], v[154:157], v[202:205], v[92:95]
	v_mfma_f32_16x16x32_bf16 v[84:87], v[162:165], v[202:205], v[84:87]
	v_mfma_f32_16x16x32_bf16 v[76:79], v[154:157], v[210:213], v[76:79]
	v_mfma_f32_16x16x32_bf16 v[68:71], v[162:165], v[210:213], v[68:71]
	s_setprio 0
	s_setprio 1
	v_mfma_f32_16x16x32_bf16 v[120:123], v[166:169], v[182:185], v[120:123]
	v_mfma_f32_16x16x32_bf16 v[112:115], v[174:177], v[182:185], v[112:115]
	v_mfma_f32_16x16x32_bf16 v[104:107], v[166:169], v[190:193], v[104:107]
	v_mfma_f32_16x16x32_bf16 v[96:99], v[174:177], v[190:193], v[96:99]
	v_mfma_f32_16x16x32_bf16 v[88:91], v[166:169], v[198:201], v[88:91]
	v_mfma_f32_16x16x32_bf16 v[80:83], v[174:177], v[198:201], v[80:83]
	v_mfma_f32_16x16x32_bf16 v[72:75], v[166:169], v[206:209], v[72:75]
	v_mfma_f32_16x16x32_bf16 v[64:67], v[174:177], v[206:209], v[64:67]
	v_mfma_f32_16x16x32_bf16 v[120:123], v[170:173], v[186:189], v[120:123]
	v_mfma_f32_16x16x32_bf16 v[112:115], v[178:181], v[186:189], v[112:115]
	v_mfma_f32_16x16x32_bf16 v[104:107], v[170:173], v[194:197], v[104:107]
	v_mfma_f32_16x16x32_bf16 v[96:99], v[178:181], v[194:197], v[96:99]
	v_mfma_f32_16x16x32_bf16 v[88:91], v[170:173], v[202:205], v[88:91]
	v_mfma_f32_16x16x32_bf16 v[80:83], v[178:181], v[202:205], v[80:83]
	v_mfma_f32_16x16x32_bf16 v[72:75], v[170:173], v[210:213], v[72:75]
	v_mfma_f32_16x16x32_bf16 v[64:67], v[178:181], v[210:213], v[64:67]
	s_setprio 0
	s_barrier
	s_add_i32 s52, s82, s56
	v_lshl_add_u64 v[214:215], v[214:215], 0, s[10:11]
	s_mov_b32 m0, s52
	ds_read_b128 v[182:185], v149 offset:49152
	ds_read_b128 v[186:189], v149 offset:50176
	ds_read_b128 v[190:193], v149 offset:51200
	ds_read_b128 v[194:197], v149 offset:52224
	ds_read_b128 v[198:201], v149 offset:53248
	ds_read_b128 v[202:205], v149 offset:54272
	ds_read_b128 v[206:209], v149 offset:55296
	ds_read_b128 v[210:213], v149 offset:56320
	global_load_lds_dwordx4 v[214:215], off
	s_add_i32 m0, s52, 0x2000
	s_add_u32 s50, s50, 0x40080
	v_lshl_add_u64 v[214:215], v[216:217], 0, s[10:11]
	s_addc_u32 s51, s51, 0
	s_add_i32 s52, s85, s56
	global_load_lds_dwordx4 v[214:215], off
	v_lshl_add_u64 v[214:215], s[50:51], 0, v[132:133]
	s_mov_b32 m0, s52
	s_nop 0
	global_load_lds_dwordx4 v[214:215], off
	v_lshl_add_u64 v[214:215], s[50:51], 0, v[128:129]
	s_add_i32 m0, s52, 0x2000
	s_nop 0
	global_load_lds_dwordx4 v[214:215], off
	v_lshl_add_u64 v[214:215], v[218:219], 0, s[10:11]
	s_mov_b32 m0, s69
	s_nop 0
	global_load_lds_dwordx4 v[214:215], off
	v_lshl_add_u64 v[214:215], v[220:221], 0, s[10:11]
	s_mov_b32 m0, s70
	s_nop 0
	global_load_lds_dwordx4 v[214:215], off
	s_waitcnt vmcnt(8)
	s_waitcnt lgkmcnt(0)
	s_barrier
	s_setprio 1
	s_waitcnt lgkmcnt(0)
	v_mfma_f32_16x16x32_bf16 v[60:63], v[150:153], v[182:185], v[60:63]
	v_mfma_f32_16x16x32_bf16 v[52:55], v[158:161], v[182:185], v[52:55]
	v_mfma_f32_16x16x32_bf16 v[44:47], v[150:153], v[190:193], v[44:47]
	v_mfma_f32_16x16x32_bf16 v[36:39], v[158:161], v[190:193], v[36:39]
	v_mfma_f32_16x16x32_bf16 v[28:31], v[150:153], v[198:201], v[28:31]
	v_mfma_f32_16x16x32_bf16 v[20:23], v[158:161], v[198:201], v[20:23]
	v_mfma_f32_16x16x32_bf16 v[12:15], v[150:153], v[206:209], v[12:15]
	v_mfma_f32_16x16x32_bf16 v[4:7], v[158:161], v[206:209], v[4:7]
	v_mfma_f32_16x16x32_bf16 v[60:63], v[154:157], v[186:189], v[60:63]
	v_mfma_f32_16x16x32_bf16 v[52:55], v[162:165], v[186:189], v[52:55]
	v_mfma_f32_16x16x32_bf16 v[44:47], v[154:157], v[194:197], v[44:47]
	v_mfma_f32_16x16x32_bf16 v[36:39], v[162:165], v[194:197], v[36:39]
	v_mfma_f32_16x16x32_bf16 v[28:31], v[154:157], v[202:205], v[28:31]
	v_mfma_f32_16x16x32_bf16 v[20:23], v[162:165], v[202:205], v[20:23]
	v_mfma_f32_16x16x32_bf16 v[12:15], v[154:157], v[210:213], v[12:15]
	v_mfma_f32_16x16x32_bf16 v[4:7], v[162:165], v[210:213], v[4:7]
	s_setprio 0
	s_setprio 1
	v_mfma_f32_16x16x32_bf16 v[56:59], v[166:169], v[182:185], v[56:59]
	v_mfma_f32_16x16x32_bf16 v[48:51], v[174:177], v[182:185], v[48:51]
	v_mfma_f32_16x16x32_bf16 v[40:43], v[166:169], v[190:193], v[40:43]
	v_mfma_f32_16x16x32_bf16 v[32:35], v[174:177], v[190:193], v[32:35]
	v_mfma_f32_16x16x32_bf16 v[24:27], v[166:169], v[198:201], v[24:27]
	v_mfma_f32_16x16x32_bf16 v[16:19], v[174:177], v[198:201], v[16:19]
	v_mfma_f32_16x16x32_bf16 v[8:11], v[166:169], v[206:209], v[8:11]
	v_mfma_f32_16x16x32_bf16 v[0:3], v[174:177], v[206:209], v[0:3]
	v_mfma_f32_16x16x32_bf16 v[56:59], v[170:173], v[186:189], v[56:59]
	v_mfma_f32_16x16x32_bf16 v[48:51], v[178:181], v[186:189], v[48:51]
	v_mfma_f32_16x16x32_bf16 v[40:43], v[170:173], v[194:197], v[40:43]
	v_mfma_f32_16x16x32_bf16 v[32:35], v[178:181], v[194:197], v[32:35]
	v_mfma_f32_16x16x32_bf16 v[24:27], v[170:173], v[202:205], v[24:27]
	v_mfma_f32_16x16x32_bf16 v[16:19], v[178:181], v[202:205], v[16:19]
	v_mfma_f32_16x16x32_bf16 v[8:11], v[170:173], v[210:213], v[8:11]
	v_mfma_f32_16x16x32_bf16 v[0:3], v[178:181], v[210:213], v[0:3]
	s_setprio 0
	s_barrier
	s_add_i32 s81, s81, 2
	s_add_u32 s48, s48, 0x100
	s_addc_u32 s49, s49, 0
	s_add_u32 s79, s79, 0x100
	s_addc_u32 s80, s80, 0
	s_cmp_gt_u32 s81, 13

.LBB0_220:
	s_add_u32 s95, s52, 0x100
	s_addc_u32 s96, s53, 0
	s_mov_b32 s97, -2
	ds_read_b128 v[88:91], v233
	ds_read_b128 v[92:95], v233 offset:1024
	ds_read_b128 v[112:115], v233 offset:2048
	ds_read_b128 v[116:119], v233 offset:3072
	ds_read_b128 v[132:135], v234
	ds_read_b128 v[136:139], v234 offset:1024
	ds_read_b128 v[152:155], v234 offset:2048
	ds_read_b128 v[156:159], v234 offset:3072
	s_add_u32 s52, s50, 0x100
	s_addc_u32 s53, s51, 0
	s_cmp_eq_u32 s97, 40
	s_cselect_b32 s57, s9, s53
	s_cselect_b32 s56, s8, s52
	s_cselect_b32 s55, s41, s96
	s_cselect_b32 s54, s40, s95
	v_lshl_add_u64 v[216:217], s[50:51], 0, v[196:197]
	s_add_i32 m0, s67, 0xc000
	ds_read_b128 v[160:163], v235
	ds_read_b128 v[164:167], v235 offset:1024
	ds_read_b128 v[168:171], v235 offset:2048
	ds_read_b128 v[172:175], v235 offset:3072
	ds_read_b128 v[176:179], v235 offset:4096
	ds_read_b128 v[180:183], v235 offset:5120
	ds_read_b128 v[208:211], v235 offset:6144
	ds_read_b128 v[212:215], v235 offset:7168
	global_load_lds_dwordx4 v[216:217], off
	v_lshl_add_u64 v[216:217], s[50:51], 0, v[198:199]
	s_add_i32 m0, s67, 0xe000
	s_nop 0
	global_load_lds_dwordx4 v[216:217], off
	s_waitcnt vmcnt(8)
	s_waitcnt lgkmcnt(0)
	s_barrier
	s_setprio 1
	s_waitcnt lgkmcnt(0)
	v_mfma_f32_16x16x32_bf16 v[148:151], v[88:91], v[160:163], 0
	v_mfma_f32_16x16x32_bf16 v[144:147], v[112:115], v[160:163], 0
	v_mfma_f32_16x16x32_bf16 v[124:127], v[88:91], v[168:171], 0
	v_mfma_f32_16x16x32_bf16 v[120:123], v[112:115], v[168:171], 0
	v_mfma_f32_16x16x32_bf16 v[100:103], v[88:91], v[176:179], 0
	v_mfma_f32_16x16x32_bf16 v[96:99], v[112:115], v[176:179], 0
	v_mfma_f32_16x16x32_bf16 v[76:79], v[88:91], v[208:211], 0
	v_mfma_f32_16x16x32_bf16 v[72:75], v[112:115], v[208:211], 0
	v_mfma_f32_16x16x32_bf16 v[148:151], v[92:95], v[164:167], v[148:151]
	v_mfma_f32_16x16x32_bf16 v[144:147], v[116:119], v[164:167], v[144:147]
	v_mfma_f32_16x16x32_bf16 v[124:127], v[92:95], v[172:175], v[124:127]
	v_mfma_f32_16x16x32_bf16 v[120:123], v[116:119], v[172:175], v[120:123]
	v_mfma_f32_16x16x32_bf16 v[100:103], v[92:95], v[180:183], v[100:103]
	v_mfma_f32_16x16x32_bf16 v[96:99], v[116:119], v[180:183], v[96:99]
	v_mfma_f32_16x16x32_bf16 v[76:79], v[92:95], v[212:215], v[76:79]
	v_mfma_f32_16x16x32_bf16 v[72:75], v[116:119], v[212:215], v[72:75]
	s_setprio 0
	s_setprio 1
	v_mfma_f32_16x16x32_bf16 v[140:143], v[132:135], v[160:163], 0
	v_mfma_f32_16x16x32_bf16 v[128:131], v[152:155], v[160:163], 0
	v_mfma_f32_16x16x32_bf16 v[108:111], v[132:135], v[168:171], 0
	v_mfma_f32_16x16x32_bf16 v[104:107], v[152:155], v[168:171], 0
	v_mfma_f32_16x16x32_bf16 v[84:87], v[132:135], v[176:179], 0
	v_mfma_f32_16x16x32_bf16 v[80:83], v[152:155], v[176:179], 0
	v_mfma_f32_16x16x32_bf16 v[68:71], v[132:135], v[208:211], 0
	v_mfma_f32_16x16x32_bf16 v[64:67], v[152:155], v[208:211], 0
	v_mfma_f32_16x16x32_bf16 v[140:143], v[136:139], v[164:167], v[140:143]
	v_mfma_f32_16x16x32_bf16 v[128:131], v[156:159], v[164:167], v[128:131]
	v_mfma_f32_16x16x32_bf16 v[108:111], v[136:139], v[172:175], v[108:111]
	v_mfma_f32_16x16x32_bf16 v[104:107], v[156:159], v[172:175], v[104:107]
	v_mfma_f32_16x16x32_bf16 v[84:87], v[136:139], v[180:183], v[84:87]
	v_mfma_f32_16x16x32_bf16 v[80:83], v[156:159], v[180:183], v[80:83]
	v_mfma_f32_16x16x32_bf16 v[68:71], v[136:139], v[212:215], v[68:71]
	v_mfma_f32_16x16x32_bf16 v[64:67], v[156:159], v[212:215], v[64:67]
	s_setprio 0
	s_barrier
	s_add_i32 s50, s82, s66
	v_lshl_add_u64 v[216:217], s[54:55], 0, v[186:187]
	s_mov_b32 m0, s50
	ds_read_b128 v[160:163], v235 offset:16384
	ds_read_b128 v[164:167], v235 offset:17408
	ds_read_b128 v[168:171], v235 offset:18432
	ds_read_b128 v[172:175], v235 offset:19456
	ds_read_b128 v[176:179], v235 offset:20480
	ds_read_b128 v[180:183], v235 offset:21504
	ds_read_b128 v[208:211], v235 offset:22528
	ds_read_b128 v[212:215], v235 offset:23552
	global_load_lds_dwordx4 v[216:217], off
	s_add_i32 m0, s50, 0x2000
	s_add_u32 s50, s54, 0xb0000
	v_lshl_add_u64 v[218:219], s[54:55], 0, v[190:191]
	s_addc_u32 s51, s55, 0
	s_add_i32 vcc_lo, s85, s66
	global_load_lds_dwordx4 v[218:219], off
	v_lshl_add_u64 v[220:221], s[50:51], 0, v[186:187]
	s_mov_b32 m0, vcc_lo
	v_lshl_add_u64 v[222:223], s[56:57], 0, v[188:189]
	global_load_lds_dwordx4 v[220:221], off
	v_lshl_add_u64 v[220:221], s[50:51], 0, v[190:191]
	s_add_i32 m0, vcc_lo, 0x2000
	s_nop 0
	global_load_lds_dwordx4 v[220:221], off
	v_lshl_add_u64 v[220:221], s[56:57], 0, v[184:185]
	s_mov_b32 m0, s67
	s_nop 0
	global_load_lds_dwordx4 v[220:221], off
	s_mov_b32 m0, s68
	s_nop 0
	global_load_lds_dwordx4 v[222:223], off
	s_waitcnt vmcnt(8)
	s_waitcnt lgkmcnt(0)
	s_barrier
	s_setprio 1
	s_waitcnt lgkmcnt(0)
	v_mfma_f32_16x16x32_bf16 v[60:63], v[88:91], v[160:163], 0
	v_mfma_f32_16x16x32_bf16 v[56:59], v[112:115], v[160:163], 0
	v_mfma_f32_16x16x32_bf16 v[44:47], v[88:91], v[168:171], 0
	v_mfma_f32_16x16x32_bf16 v[40:43], v[112:115], v[168:171], 0
	v_mfma_f32_16x16x32_bf16 v[28:31], v[88:91], v[176:179], 0
	v_mfma_f32_16x16x32_bf16 v[24:27], v[112:115], v[176:179], 0
	v_mfma_f32_16x16x32_bf16 v[12:15], v[88:91], v[208:211], 0
	v_mfma_f32_16x16x32_bf16 v[8:11], v[112:115], v[208:211], 0
	v_mfma_f32_16x16x32_bf16 v[60:63], v[92:95], v[164:167], v[60:63]
	v_mfma_f32_16x16x32_bf16 v[56:59], v[116:119], v[164:167], v[56:59]
	v_mfma_f32_16x16x32_bf16 v[44:47], v[92:95], v[172:175], v[44:47]
	v_mfma_f32_16x16x32_bf16 v[40:43], v[116:119], v[172:175], v[40:43]
	v_mfma_f32_16x16x32_bf16 v[28:31], v[92:95], v[180:183], v[28:31]
	v_mfma_f32_16x16x32_bf16 v[24:27], v[116:119], v[180:183], v[24:27]
	v_mfma_f32_16x16x32_bf16 v[12:15], v[92:95], v[212:215], v[12:15]
	v_mfma_f32_16x16x32_bf16 v[8:11], v[116:119], v[212:215], v[8:11]
	s_setprio 0
	s_setprio 1
	v_mfma_f32_16x16x32_bf16 v[52:55], v[132:135], v[160:163], 0
	v_mfma_f32_16x16x32_bf16 v[48:51], v[152:155], v[160:163], 0
	v_mfma_f32_16x16x32_bf16 v[36:39], v[132:135], v[168:171], 0
	v_mfma_f32_16x16x32_bf16 v[32:35], v[152:155], v[168:171], 0
	v_mfma_f32_16x16x32_bf16 v[20:23], v[132:135], v[176:179], 0
	v_mfma_f32_16x16x32_bf16 v[16:19], v[152:155], v[176:179], 0
	v_mfma_f32_16x16x32_bf16 v[4:7], v[132:135], v[208:211], 0
	v_mfma_f32_16x16x32_bf16 v[0:3], v[152:155], v[208:211], 0
	v_mfma_f32_16x16x32_bf16 v[52:55], v[136:139], v[164:167], v[52:55]
	v_mfma_f32_16x16x32_bf16 v[48:51], v[156:159], v[164:167], v[48:51]
	v_mfma_f32_16x16x32_bf16 v[36:39], v[136:139], v[172:175], v[36:39]
	v_mfma_f32_16x16x32_bf16 v[32:35], v[156:159], v[172:175], v[32:35]
	v_mfma_f32_16x16x32_bf16 v[20:23], v[136:139], v[180:183], v[20:23]
	v_mfma_f32_16x16x32_bf16 v[16:19], v[156:159], v[180:183], v[16:19]
	v_mfma_f32_16x16x32_bf16 v[4:7], v[136:139], v[212:215], v[4:7]
	v_mfma_f32_16x16x32_bf16 v[0:3], v[156:159], v[212:215], v[0:3]
	s_setprio 0
	s_barrier
	s_add_i32 vcc_lo, 0, 0x18000
	s_add_i32 vcc_hi, 0, 0x1c000
	v_add_u32_e32 v116, vcc_lo, v230
	v_add_u32_e32 v156, vcc_hi, v230
	ds_read_b128 v[88:91], v116
	ds_read_b128 v[92:95], v116 offset:1024
	ds_read_b128 v[112:115], v116 offset:2048
	ds_read_b128 v[116:119], v116 offset:3072
	ds_read_b128 v[132:135], v156
	ds_read_b128 v[136:139], v156 offset:1024
	ds_read_b128 v[152:155], v156 offset:2048
	ds_read_b128 v[156:159], v156 offset:3072
	s_add_u32 s50, s56, 0xb0000
	s_addc_u32 s51, s57, 0
	s_mov_b32 m0, s69
	v_lshl_add_u64 v[224:225], s[50:51], 0, v[184:185]
	ds_read_b128 v[160:163], v235 offset:32768
	ds_read_b128 v[164:167], v235 offset:33792
	ds_read_b128 v[168:171], v235 offset:34816
	ds_read_b128 v[172:175], v235 offset:35840
	ds_read_b128 v[176:179], v235 offset:36864
	ds_read_b128 v[180:183], v235 offset:37888
	ds_read_b128 v[208:211], v235 offset:38912
	ds_read_b128 v[212:215], v235 offset:39936
	global_load_lds_dwordx4 v[224:225], off
	v_lshl_add_u64 v[224:225], s[50:51], 0, v[188:189]
	s_mov_b32 m0, s70
	s_nop 0
	global_load_lds_dwordx4 v[224:225], off
	s_waitcnt vmcnt(8)
	s_waitcnt lgkmcnt(0)
	s_barrier
	s_setprio 1
	s_waitcnt lgkmcnt(0)
	v_mfma_f32_16x16x32_bf16 v[148:151], v[88:91], v[160:163], v[148:151]
	v_mfma_f32_16x16x32_bf16 v[144:147], v[112:115], v[160:163], v[144:147]
	v_mfma_f32_16x16x32_bf16 v[124:127], v[88:91], v[168:171], v[124:127]
	v_mfma_f32_16x16x32_bf16 v[120:123], v[112:115], v[168:171], v[120:123]
	v_mfma_f32_16x16x32_bf16 v[100:103], v[88:91], v[176:179], v[100:103]
	v_mfma_f32_16x16x32_bf16 v[96:99], v[112:115], v[176:179], v[96:99]
	v_mfma_f32_16x16x32_bf16 v[76:79], v[88:91], v[208:211], v[76:79]
	v_mfma_f32_16x16x32_bf16 v[72:75], v[112:115], v[208:211], v[72:75]
	v_mfma_f32_16x16x32_bf16 v[148:151], v[92:95], v[164:167], v[148:151]
	v_mfma_f32_16x16x32_bf16 v[144:147], v[116:119], v[164:167], v[144:147]
	v_mfma_f32_16x16x32_bf16 v[124:127], v[92:95], v[172:175], v[124:127]
	v_mfma_f32_16x16x32_bf16 v[120:123], v[116:119], v[172:175], v[120:123]
	v_mfma_f32_16x16x32_bf16 v[100:103], v[92:95], v[180:183], v[100:103]
	v_mfma_f32_16x16x32_bf16 v[96:99], v[116:119], v[180:183], v[96:99]
	v_mfma_f32_16x16x32_bf16 v[76:79], v[92:95], v[212:215], v[76:79]
	v_mfma_f32_16x16x32_bf16 v[72:75], v[116:119], v[212:215], v[72:75]
	s_setprio 0
	s_setprio 1
	v_mfma_f32_16x16x32_bf16 v[140:143], v[132:135], v[160:163], v[140:143]
	v_mfma_f32_16x16x32_bf16 v[128:131], v[152:155], v[160:163], v[128:131]
	v_mfma_f32_16x16x32_bf16 v[108:111], v[132:135], v[168:171], v[108:111]
	v_mfma_f32_16x16x32_bf16 v[104:107], v[152:155], v[168:171], v[104:107]
	v_mfma_f32_16x16x32_bf16 v[84:87], v[132:135], v[176:179], v[84:87]
	v_mfma_f32_16x16x32_bf16 v[80:83], v[152:155], v[176:179], v[80:83]
	v_mfma_f32_16x16x32_bf16 v[68:71], v[132:135], v[208:211], v[68:71]
	v_mfma_f32_16x16x32_bf16 v[64:67], v[152:155], v[208:211], v[64:67]
	v_mfma_f32_16x16x32_bf16 v[140:143], v[136:139], v[164:167], v[140:143]
	v_mfma_f32_16x16x32_bf16 v[128:131], v[156:159], v[164:167], v[128:131]
	v_mfma_f32_16x16x32_bf16 v[108:111], v[136:139], v[172:175], v[108:111]
	v_mfma_f32_16x16x32_bf16 v[104:107], v[156:159], v[172:175], v[104:107]
	v_mfma_f32_16x16x32_bf16 v[84:87], v[136:139], v[180:183], v[84:87]
	v_mfma_f32_16x16x32_bf16 v[80:83], v[156:159], v[180:183], v[80:83]
	v_mfma_f32_16x16x32_bf16 v[68:71], v[136:139], v[212:215], v[68:71]
	v_mfma_f32_16x16x32_bf16 v[64:67], v[156:159], v[212:215], v[64:67]
	s_setprio 0
	s_barrier
	s_add_i32 s50, vcc_lo, s66
	v_lshl_add_u64 v[216:217], v[216:217], 0, s[46:47]
	s_mov_b32 m0, s50
	ds_read_b128 v[160:163], v235 offset:49152
	ds_read_b128 v[164:167], v235 offset:50176
	ds_read_b128 v[168:171], v235 offset:51200
	ds_read_b128 v[172:175], v235 offset:52224
	ds_read_b128 v[176:179], v235 offset:53248
	ds_read_b128 v[180:183], v235 offset:54272
	ds_read_b128 v[208:211], v235 offset:55296
	ds_read_b128 v[212:215], v235 offset:56320
	global_load_lds_dwordx4 v[216:217], off
	s_add_i32 m0, s50, 0x2000
	s_add_u32 s50, s54, 0xb0080
	v_lshl_add_u64 v[216:217], v[218:219], 0, s[46:47]
	s_addc_u32 s51, s55, 0
	s_add_i32 s54, vcc_hi, s66
	global_load_lds_dwordx4 v[216:217], off
	v_lshl_add_u64 v[216:217], s[50:51], 0, v[186:187]
	s_mov_b32 m0, s54
	s_nop 0
	global_load_lds_dwordx4 v[216:217], off
	v_lshl_add_u64 v[216:217], s[50:51], 0, v[190:191]
	s_add_i32 m0, s54, 0x2000
	s_nop 0
	global_load_lds_dwordx4 v[216:217], off
	v_lshl_add_u64 v[216:217], v[220:221], 0, s[46:47]
	s_mov_b32 m0, s74
	s_nop 0
	global_load_lds_dwordx4 v[216:217], off
	v_lshl_add_u64 v[216:217], v[222:223], 0, s[46:47]
	s_mov_b32 m0, s75
	s_nop 0
	global_load_lds_dwordx4 v[216:217], off
	s_waitcnt vmcnt(8)
	s_waitcnt lgkmcnt(0)
	s_barrier
	s_setprio 1
	s_waitcnt lgkmcnt(0)
	v_mfma_f32_16x16x32_bf16 v[60:63], v[88:91], v[160:163], v[60:63]
	v_mfma_f32_16x16x32_bf16 v[56:59], v[112:115], v[160:163], v[56:59]
	v_mfma_f32_16x16x32_bf16 v[44:47], v[88:91], v[168:171], v[44:47]
	v_mfma_f32_16x16x32_bf16 v[40:43], v[112:115], v[168:171], v[40:43]
	v_mfma_f32_16x16x32_bf16 v[28:31], v[88:91], v[176:179], v[28:31]
	v_mfma_f32_16x16x32_bf16 v[24:27], v[112:115], v[176:179], v[24:27]
	v_mfma_f32_16x16x32_bf16 v[12:15], v[88:91], v[208:211], v[12:15]
	v_mfma_f32_16x16x32_bf16 v[8:11], v[112:115], v[208:211], v[8:11]
	v_mfma_f32_16x16x32_bf16 v[60:63], v[92:95], v[164:167], v[60:63]
	v_mfma_f32_16x16x32_bf16 v[56:59], v[116:119], v[164:167], v[56:59]
	v_mfma_f32_16x16x32_bf16 v[44:47], v[92:95], v[172:175], v[44:47]
	v_mfma_f32_16x16x32_bf16 v[40:43], v[116:119], v[172:175], v[40:43]
	v_mfma_f32_16x16x32_bf16 v[28:31], v[92:95], v[180:183], v[28:31]
	v_mfma_f32_16x16x32_bf16 v[24:27], v[116:119], v[180:183], v[24:27]
	v_mfma_f32_16x16x32_bf16 v[12:15], v[92:95], v[212:215], v[12:15]
	v_mfma_f32_16x16x32_bf16 v[8:11], v[116:119], v[212:215], v[8:11]
	s_setprio 0
	s_setprio 1
	v_mfma_f32_16x16x32_bf16 v[52:55], v[132:135], v[160:163], v[52:55]
	v_mfma_f32_16x16x32_bf16 v[48:51], v[152:155], v[160:163], v[48:51]
	v_mfma_f32_16x16x32_bf16 v[36:39], v[132:135], v[168:171], v[36:39]
	v_mfma_f32_16x16x32_bf16 v[32:35], v[152:155], v[168:171], v[32:35]
	v_mfma_f32_16x16x32_bf16 v[20:23], v[132:135], v[176:179], v[20:23]
	v_mfma_f32_16x16x32_bf16 v[16:19], v[152:155], v[176:179], v[16:19]
	v_mfma_f32_16x16x32_bf16 v[4:7], v[132:135], v[208:211], v[4:7]
	v_mfma_f32_16x16x32_bf16 v[0:3], v[152:155], v[208:211], v[0:3]
	v_mfma_f32_16x16x32_bf16 v[52:55], v[136:139], v[164:167], v[52:55]
	v_mfma_f32_16x16x32_bf16 v[48:51], v[156:159], v[164:167], v[48:51]
	v_mfma_f32_16x16x32_bf16 v[36:39], v[136:139], v[172:175], v[36:39]
	v_mfma_f32_16x16x32_bf16 v[32:35], v[156:159], v[172:175], v[32:35]
	v_mfma_f32_16x16x32_bf16 v[20:23], v[136:139], v[180:183], v[20:23]
	v_mfma_f32_16x16x32_bf16 v[16:19], v[156:159], v[180:183], v[16:19]
	v_mfma_f32_16x16x32_bf16 v[4:7], v[136:139], v[212:215], v[4:7]
	v_mfma_f32_16x16x32_bf16 v[0:3], v[156:159], v[212:215], v[0:3]
	s_setprio 0
	s_barrier
	s_add_i32 s97, s97, 2
	s_add_u32 s95, s95, 0x100
	s_addc_u32 s96, s96, 0
	s_cmp_gt_u32 s97, 41
	s_mov_b64 s[50:51], s[52:53]

.LBB0_312:
	s_ashr_i32 s43, s42, 31
	s_lshl_b64 s[46:47], s[42:43], 19
	s_add_u32 s46, s62, s46
	s_addc_u32 s47, s63, s47
	s_and_b64 s[48:49], s[4:5], exec
	s_cselect_b32 s10, s47, s53
	s_cselect_b32 s43, s46, s52
	s_ashr_i32 s45, s44, 31
	s_lshl_b64 s[48:49], s[44:45], 19
	s_add_u32 s48, s70, s48
	s_addc_u32 s49, s71, s49
	s_and_b64 s[56:57], s[4:5], exec
	s_cselect_b32 s45, s49, s55
	s_cselect_b32 s51, s48, s54
	s_add_u32 s52, s52, 0x40080
	s_addc_u32 s53, s53, 0
	s_add_u32 s67, s54, 0x100
	s_addc_u32 s68, s55, 0
	s_mov_b32 s69, -2
	ds_read_b128 v[128:131], v179
	ds_read_b128 v[132:135], v179 offset:1024
	ds_read_b128 v[136:139], v179 offset:2048
	ds_read_b128 v[140:143], v179 offset:3072
	ds_read_b128 v[188:191], v181
	ds_read_b128 v[192:195], v181 offset:1024
	ds_read_b128 v[196:199], v181 offset:2048
	ds_read_b128 v[200:203], v181 offset:3072
	s_add_u32 s54, s52, 0xfffc0080
	s_addc_u32 s55, s53, -1
	s_cmp_eq_u32 s69, 12
	s_cselect_b32 s57, s10, s55
	s_cselect_b32 s56, s43, s54
	s_cselect_b32 s55, s45, s68
	s_cselect_b32 s54, s51, s67
	v_lshl_add_u64 v[238:239], s[52:53], 0, v[162:163]
	s_add_i32 m0, s75, 0xc000
	ds_read_b128 v[204:207], v183
	ds_read_b128 v[208:211], v183 offset:1024
	ds_read_b128 v[212:215], v183 offset:2048
	ds_read_b128 v[216:219], v183 offset:3072
	ds_read_b128 v[220:223], v183 offset:4096
	ds_read_b128 v[224:227], v183 offset:5120
	ds_read_b128 v[230:233], v183 offset:6144
	ds_read_b128 v[234:237], v183 offset:7168
	global_load_lds_dwordx4 v[238:239], off
	v_lshl_add_u64 v[238:239], s[52:53], 0, v[164:165]
	s_add_i32 m0, s75, 0xe000
	s_nop 0
	global_load_lds_dwordx4 v[238:239], off
	s_waitcnt vmcnt(8)
	s_waitcnt lgkmcnt(0)
	s_barrier
	s_setprio 1
	s_waitcnt lgkmcnt(0)
	v_mfma_f32_16x16x32_bf16 v[124:127], v[128:131], v[204:207], 0
	v_mfma_f32_16x16x32_bf16 v[120:123], v[136:139], v[204:207], 0
	v_mfma_f32_16x16x32_bf16 v[108:111], v[128:131], v[212:215], 0
	v_mfma_f32_16x16x32_bf16 v[104:107], v[136:139], v[212:215], 0
	v_mfma_f32_16x16x32_bf16 v[92:95], v[128:131], v[220:223], 0
	v_mfma_f32_16x16x32_bf16 v[88:91], v[136:139], v[220:223], 0
	v_mfma_f32_16x16x32_bf16 v[76:79], v[128:131], v[230:233], 0
	v_mfma_f32_16x16x32_bf16 v[72:75], v[136:139], v[230:233], 0
	v_mfma_f32_16x16x32_bf16 v[124:127], v[132:135], v[208:211], v[124:127]
	v_mfma_f32_16x16x32_bf16 v[120:123], v[140:143], v[208:211], v[120:123]
	v_mfma_f32_16x16x32_bf16 v[108:111], v[132:135], v[216:219], v[108:111]
	v_mfma_f32_16x16x32_bf16 v[104:107], v[140:143], v[216:219], v[104:107]
	v_mfma_f32_16x16x32_bf16 v[92:95], v[132:135], v[224:227], v[92:95]
	v_mfma_f32_16x16x32_bf16 v[88:91], v[140:143], v[224:227], v[88:91]
	v_mfma_f32_16x16x32_bf16 v[76:79], v[132:135], v[234:237], v[76:79]
	v_mfma_f32_16x16x32_bf16 v[72:75], v[140:143], v[234:237], v[72:75]
	s_setprio 0
	s_setprio 1
	v_mfma_f32_16x16x32_bf16 v[116:119], v[188:191], v[204:207], 0
	v_mfma_f32_16x16x32_bf16 v[112:115], v[196:199], v[204:207], 0
	v_mfma_f32_16x16x32_bf16 v[100:103], v[188:191], v[212:215], 0
	v_mfma_f32_16x16x32_bf16 v[96:99], v[196:199], v[212:215], 0
	v_mfma_f32_16x16x32_bf16 v[84:87], v[188:191], v[220:223], 0
	v_mfma_f32_16x16x32_bf16 v[80:83], v[196:199], v[220:223], 0
	v_mfma_f32_16x16x32_bf16 v[68:71], v[188:191], v[230:233], 0
	v_mfma_f32_16x16x32_bf16 v[64:67], v[196:199], v[230:233], 0
	v_mfma_f32_16x16x32_bf16 v[116:119], v[192:195], v[208:211], v[116:119]
	v_mfma_f32_16x16x32_bf16 v[112:115], v[200:203], v[208:211], v[112:115]
	v_mfma_f32_16x16x32_bf16 v[100:103], v[192:195], v[216:219], v[100:103]
	v_mfma_f32_16x16x32_bf16 v[96:99], v[200:203], v[216:219], v[96:99]
	v_mfma_f32_16x16x32_bf16 v[84:87], v[192:195], v[224:227], v[84:87]
	v_mfma_f32_16x16x32_bf16 v[80:83], v[200:203], v[224:227], v[80:83]
	v_mfma_f32_16x16x32_bf16 v[68:71], v[192:195], v[234:237], v[68:71]
	v_mfma_f32_16x16x32_bf16 v[64:67], v[200:203], v[234:237], v[64:67]
	s_setprio 0
	s_barrier
	s_add_i32 vcc_lo, s92, s72
	v_lshl_add_u64 v[238:239], s[54:55], 0, v[148:149]
	s_mov_b32 m0, vcc_lo
	ds_read_b128 v[204:207], v183 offset:16384
	ds_read_b128 v[208:211], v183 offset:17408
	ds_read_b128 v[212:215], v183 offset:18432
	ds_read_b128 v[216:219], v183 offset:19456
	ds_read_b128 v[220:223], v183 offset:20480
	ds_read_b128 v[224:227], v183 offset:21504
	ds_read_b128 v[230:233], v183 offset:22528
	ds_read_b128 v[234:237], v183 offset:23552
	global_load_lds_dwordx4 v[238:239], off
	s_add_i32 m0, vcc_lo, 0x2000
	s_add_u32 vcc_lo, s54, 0x40000
	v_lshl_add_u64 v[240:241], s[54:55], 0, v[144:145]
	s_addc_u32 vcc_hi, s55, 0
	s_add_i32 s83, s93, s72
	global_load_lds_dwordx4 v[240:241], off
	v_lshl_add_u64 v[242:243], vcc, 0, v[148:149]
	s_mov_b32 m0, s83
	v_lshl_add_u64 v[244:245], s[56:57], 0, v[146:147]
	global_load_lds_dwordx4 v[242:243], off
	v_lshl_add_u64 v[242:243], vcc, 0, v[144:145]
	s_add_i32 m0, s83, 0x2000
	s_nop 0
	global_load_lds_dwordx4 v[242:243], off
	v_lshl_add_u64 v[242:243], s[56:57], 0, v[150:151]
	s_mov_b32 m0, s75
	s_nop 0
	global_load_lds_dwordx4 v[242:243], off
	s_mov_b32 m0, s76
	s_nop 0
	global_load_lds_dwordx4 v[244:245], off
	s_waitcnt vmcnt(8)
	s_waitcnt lgkmcnt(0)
	s_barrier
	s_setprio 1
	s_waitcnt lgkmcnt(0)
	v_mfma_f32_16x16x32_bf16 v[60:63], v[128:131], v[204:207], 0
	v_mfma_f32_16x16x32_bf16 v[56:59], v[136:139], v[204:207], 0
	v_mfma_f32_16x16x32_bf16 v[44:47], v[128:131], v[212:215], 0
	v_mfma_f32_16x16x32_bf16 v[40:43], v[136:139], v[212:215], 0
	v_mfma_f32_16x16x32_bf16 v[28:31], v[128:131], v[220:223], 0
	v_mfma_f32_16x16x32_bf16 v[24:27], v[136:139], v[220:223], 0
	v_mfma_f32_16x16x32_bf16 v[12:15], v[128:131], v[230:233], 0
	v_mfma_f32_16x16x32_bf16 v[8:11], v[136:139], v[230:233], 0
	v_mfma_f32_16x16x32_bf16 v[60:63], v[132:135], v[208:211], v[60:63]
	v_mfma_f32_16x16x32_bf16 v[56:59], v[140:143], v[208:211], v[56:59]
	v_mfma_f32_16x16x32_bf16 v[44:47], v[132:135], v[216:219], v[44:47]
	v_mfma_f32_16x16x32_bf16 v[40:43], v[140:143], v[216:219], v[40:43]
	v_mfma_f32_16x16x32_bf16 v[28:31], v[132:135], v[224:227], v[28:31]
	v_mfma_f32_16x16x32_bf16 v[24:27], v[140:143], v[224:227], v[24:27]
	v_mfma_f32_16x16x32_bf16 v[12:15], v[132:135], v[234:237], v[12:15]
	v_mfma_f32_16x16x32_bf16 v[8:11], v[140:143], v[234:237], v[8:11]
	s_setprio 0
	s_setprio 1
	v_mfma_f32_16x16x32_bf16 v[52:55], v[188:191], v[204:207], 0
	v_mfma_f32_16x16x32_bf16 v[48:51], v[196:199], v[204:207], 0
	v_mfma_f32_16x16x32_bf16 v[36:39], v[188:191], v[212:215], 0
	v_mfma_f32_16x16x32_bf16 v[32:35], v[196:199], v[212:215], 0
	v_mfma_f32_16x16x32_bf16 v[20:23], v[188:191], v[220:223], 0
	v_mfma_f32_16x16x32_bf16 v[16:19], v[196:199], v[220:223], 0
	v_mfma_f32_16x16x32_bf16 v[4:7], v[188:191], v[230:233], 0
	v_mfma_f32_16x16x32_bf16 v[0:3], v[196:199], v[230:233], 0
	v_mfma_f32_16x16x32_bf16 v[52:55], v[192:195], v[208:211], v[52:55]
	v_mfma_f32_16x16x32_bf16 v[48:51], v[200:203], v[208:211], v[48:51]
	v_mfma_f32_16x16x32_bf16 v[36:39], v[192:195], v[216:219], v[36:39]
	v_mfma_f32_16x16x32_bf16 v[32:35], v[200:203], v[216:219], v[32:35]
	v_mfma_f32_16x16x32_bf16 v[20:23], v[192:195], v[224:227], v[20:23]
	v_mfma_f32_16x16x32_bf16 v[16:19], v[200:203], v[224:227], v[16:19]
	v_mfma_f32_16x16x32_bf16 v[4:7], v[192:195], v[234:237], v[4:7]
	v_mfma_f32_16x16x32_bf16 v[0:3], v[200:203], v[234:237], v[0:3]
	s_setprio 0
	s_barrier
	s_add_i32 s83, 0, 0x18000
	s_add_i32 vcc_lo, 0, 0x1c000
	v_add_u32_e32 v140, s83, v157
	v_add_u32_e32 v171, vcc_lo, v157
	ds_read_b128 v[128:131], v140
	ds_read_b128 v[132:135], v140 offset:1024
	ds_read_b128 v[136:139], v140 offset:2048
	ds_read_b128 v[140:143], v140 offset:3072
	ds_read_b128 v[188:191], v171
	ds_read_b128 v[192:195], v171 offset:1024
	ds_read_b128 v[196:199], v171 offset:2048
	ds_read_b128 v[200:203], v171 offset:3072
	s_add_u32 s56, s56, 0x40000
	s_addc_u32 s57, s57, 0
	s_mov_b32 m0, s77
	v_lshl_add_u64 v[246:247], s[56:57], 0, v[150:151]
	ds_read_b128 v[204:207], v183 offset:32768
	ds_read_b128 v[208:211], v183 offset:33792
	ds_read_b128 v[212:215], v183 offset:34816
	ds_read_b128 v[216:219], v183 offset:35840
	ds_read_b128 v[220:223], v183 offset:36864
	ds_read_b128 v[224:227], v183 offset:37888
	ds_read_b128 v[230:233], v183 offset:38912
	ds_read_b128 v[234:237], v183 offset:39936
	global_load_lds_dwordx4 v[246:247], off
	v_lshl_add_u64 v[246:247], s[56:57], 0, v[146:147]
	s_mov_b32 m0, s78
	s_nop 0
	global_load_lds_dwordx4 v[246:247], off
	s_waitcnt vmcnt(8)
	s_waitcnt lgkmcnt(0)
	s_barrier
	s_setprio 1
	s_waitcnt lgkmcnt(0)
	v_mfma_f32_16x16x32_bf16 v[124:127], v[128:131], v[204:207], v[124:127]
	v_mfma_f32_16x16x32_bf16 v[120:123], v[136:139], v[204:207], v[120:123]
	v_mfma_f32_16x16x32_bf16 v[108:111], v[128:131], v[212:215], v[108:111]
	v_mfma_f32_16x16x32_bf16 v[104:107], v[136:139], v[212:215], v[104:107]
	v_mfma_f32_16x16x32_bf16 v[92:95], v[128:131], v[220:223], v[92:95]
	v_mfma_f32_16x16x32_bf16 v[88:91], v[136:139], v[220:223], v[88:91]
	v_mfma_f32_16x16x32_bf16 v[76:79], v[128:131], v[230:233], v[76:79]
	v_mfma_f32_16x16x32_bf16 v[72:75], v[136:139], v[230:233], v[72:75]
	v_mfma_f32_16x16x32_bf16 v[124:127], v[132:135], v[208:211], v[124:127]
	v_mfma_f32_16x16x32_bf16 v[120:123], v[140:143], v[208:211], v[120:123]
	v_mfma_f32_16x16x32_bf16 v[108:111], v[132:135], v[216:219], v[108:111]
	v_mfma_f32_16x16x32_bf16 v[104:107], v[140:143], v[216:219], v[104:107]
	v_mfma_f32_16x16x32_bf16 v[92:95], v[132:135], v[224:227], v[92:95]
	v_mfma_f32_16x16x32_bf16 v[88:91], v[140:143], v[224:227], v[88:91]
	v_mfma_f32_16x16x32_bf16 v[76:79], v[132:135], v[234:237], v[76:79]
	v_mfma_f32_16x16x32_bf16 v[72:75], v[140:143], v[234:237], v[72:75]
	s_setprio 0
	s_setprio 1
	v_mfma_f32_16x16x32_bf16 v[116:119], v[188:191], v[204:207], v[116:119]
	v_mfma_f32_16x16x32_bf16 v[112:115], v[196:199], v[204:207], v[112:115]
	v_mfma_f32_16x16x32_bf16 v[100:103], v[188:191], v[212:215], v[100:103]
	v_mfma_f32_16x16x32_bf16 v[96:99], v[196:199], v[212:215], v[96:99]
	v_mfma_f32_16x16x32_bf16 v[84:87], v[188:191], v[220:223], v[84:87]
	v_mfma_f32_16x16x32_bf16 v[80:83], v[196:199], v[220:223], v[80:83]
	v_mfma_f32_16x16x32_bf16 v[68:71], v[188:191], v[230:233], v[68:71]
	v_mfma_f32_16x16x32_bf16 v[64:67], v[196:199], v[230:233], v[64:67]
	v_mfma_f32_16x16x32_bf16 v[116:119], v[192:195], v[208:211], v[116:119]
	v_mfma_f32_16x16x32_bf16 v[112:115], v[200:203], v[208:211], v[112:115]
	v_mfma_f32_16x16x32_bf16 v[100:103], v[192:195], v[216:219], v[100:103]
	v_mfma_f32_16x16x32_bf16 v[96:99], v[200:203], v[216:219], v[96:99]
	v_mfma_f32_16x16x32_bf16 v[84:87], v[192:195], v[224:227], v[84:87]
	v_mfma_f32_16x16x32_bf16 v[80:83], v[200:203], v[224:227], v[80:83]
	v_mfma_f32_16x16x32_bf16 v[68:71], v[192:195], v[234:237], v[68:71]
	v_mfma_f32_16x16x32_bf16 v[64:67], v[200:203], v[234:237], v[64:67]
	s_setprio 0
	s_barrier
	s_add_i32 s56, s83, s72
	v_lshl_add_u64 v[238:239], v[238:239], 0, s[38:39]
	s_mov_b32 m0, s56
	ds_read_b128 v[204:207], v183 offset:49152
	ds_read_b128 v[208:211], v183 offset:50176
	ds_read_b128 v[212:215], v183 offset:51200
	ds_read_b128 v[216:219], v183 offset:52224
	ds_read_b128 v[220:223], v183 offset:53248
	ds_read_b128 v[224:227], v183 offset:54272
	ds_read_b128 v[230:233], v183 offset:55296
	ds_read_b128 v[234:237], v183 offset:56320
	global_load_lds_dwordx4 v[238:239], off
	s_add_i32 m0, s56, 0x2000
	s_add_u32 s54, s54, 0x40080
	v_lshl_add_u64 v[238:239], v[240:241], 0, s[38:39]
	s_addc_u32 s55, s55, 0
	s_add_i32 s56, vcc_lo, s72
	global_load_lds_dwordx4 v[238:239], off
	v_lshl_add_u64 v[238:239], s[54:55], 0, v[148:149]
	s_mov_b32 m0, s56
	s_nop 0
	global_load_lds_dwordx4 v[238:239], off
	v_lshl_add_u64 v[238:239], s[54:55], 0, v[144:145]
	s_add_i32 m0, s56, 0x2000
	s_nop 0
	global_load_lds_dwordx4 v[238:239], off
	v_lshl_add_u64 v[238:239], v[242:243], 0, s[38:39]
	s_mov_b32 m0, s87
	s_nop 0
	global_load_lds_dwordx4 v[238:239], off
	v_lshl_add_u64 v[238:239], v[244:245], 0, s[38:39]
	s_mov_b32 m0, s88
	s_nop 0
	global_load_lds_dwordx4 v[238:239], off
	s_waitcnt vmcnt(8)
	s_waitcnt lgkmcnt(0)
	s_barrier
	s_setprio 1
	s_waitcnt lgkmcnt(0)
	v_mfma_f32_16x16x32_bf16 v[60:63], v[128:131], v[204:207], v[60:63]
	v_mfma_f32_16x16x32_bf16 v[56:59], v[136:139], v[204:207], v[56:59]
	v_mfma_f32_16x16x32_bf16 v[44:47], v[128:131], v[212:215], v[44:47]
	v_mfma_f32_16x16x32_bf16 v[40:43], v[136:139], v[212:215], v[40:43]
	v_mfma_f32_16x16x32_bf16 v[28:31], v[128:131], v[220:223], v[28:31]
	v_mfma_f32_16x16x32_bf16 v[24:27], v[136:139], v[220:223], v[24:27]
	v_mfma_f32_16x16x32_bf16 v[12:15], v[128:131], v[230:233], v[12:15]
	v_mfma_f32_16x16x32_bf16 v[8:11], v[136:139], v[230:233], v[8:11]
	v_mfma_f32_16x16x32_bf16 v[60:63], v[132:135], v[208:211], v[60:63]
	v_mfma_f32_16x16x32_bf16 v[56:59], v[140:143], v[208:211], v[56:59]
	v_mfma_f32_16x16x32_bf16 v[44:47], v[132:135], v[216:219], v[44:47]
	v_mfma_f32_16x16x32_bf16 v[40:43], v[140:143], v[216:219], v[40:43]
	v_mfma_f32_16x16x32_bf16 v[28:31], v[132:135], v[224:227], v[28:31]
	v_mfma_f32_16x16x32_bf16 v[24:27], v[140:143], v[224:227], v[24:27]
	v_mfma_f32_16x16x32_bf16 v[12:15], v[132:135], v[234:237], v[12:15]
	v_mfma_f32_16x16x32_bf16 v[8:11], v[140:143], v[234:237], v[8:11]
	s_setprio 0
	s_setprio 1
	v_mfma_f32_16x16x32_bf16 v[52:55], v[188:191], v[204:207], v[52:55]
	v_mfma_f32_16x16x32_bf16 v[48:51], v[196:199], v[204:207], v[48:51]
	v_mfma_f32_16x16x32_bf16 v[36:39], v[188:191], v[212:215], v[36:39]
	v_mfma_f32_16x16x32_bf16 v[32:35], v[196:199], v[212:215], v[32:35]
	v_mfma_f32_16x16x32_bf16 v[20:23], v[188:191], v[220:223], v[20:23]
	v_mfma_f32_16x16x32_bf16 v[16:19], v[196:199], v[220:223], v[16:19]
	v_mfma_f32_16x16x32_bf16 v[4:7], v[188:191], v[230:233], v[4:7]
	v_mfma_f32_16x16x32_bf16 v[0:3], v[196:199], v[230:233], v[0:3]
	v_mfma_f32_16x16x32_bf16 v[52:55], v[192:195], v[208:211], v[52:55]
	v_mfma_f32_16x16x32_bf16 v[48:51], v[200:203], v[208:211], v[48:51]
	v_mfma_f32_16x16x32_bf16 v[36:39], v[192:195], v[216:219], v[36:39]
	v_mfma_f32_16x16x32_bf16 v[32:35], v[200:203], v[216:219], v[32:35]
	v_mfma_f32_16x16x32_bf16 v[20:23], v[192:195], v[224:227], v[20:23]
	v_mfma_f32_16x16x32_bf16 v[16:19], v[200:203], v[224:227], v[16:19]
	v_mfma_f32_16x16x32_bf16 v[4:7], v[192:195], v[234:237], v[4:7]
	v_mfma_f32_16x16x32_bf16 v[0:3], v[200:203], v[234:237], v[0:3]
	s_setprio 0
	s_barrier
	s_add_i32 s69, s69, 2
	s_add_u32 s52, s52, 0x100
	s_addc_u32 s53, s53, 0
	s_add_u32 s67, s67, 0x100
	s_addc_u32 s68, s68, 0
	s_cmp_gt_u32 s69, 13

.LBB0_667:
	s_ashr_i32 s23, s22, 31
	s_lshl_b64 s[38:39], s[22:23], 19
	s_add_u32 s38, s26, s38
	s_addc_u32 s39, s27, s39
	s_and_b64 s[40:41], s[6:7], exec
	s_cselect_b32 s23, s39, s45
	s_cselect_b32 s43, s38, s44
	s_ashr_i32 s37, s36, 31
	s_lshl_b64 s[40:41], s[36:37], 19
	s_add_u32 s40, s50, s40
	s_addc_u32 s41, s51, s41
	s_and_b64 s[48:49], s[6:7], exec
	s_cselect_b32 s37, s41, s47
	s_cselect_b32 s92, s40, s46
	s_add_u32 s44, s44, 0x40080
	s_addc_u32 s45, s45, 0
	s_add_u32 s93, s46, 0x100
	s_addc_u32 s94, s47, 0
	s_mov_b32 s95, -2
	s_waitcnt lgkmcnt(0)
	ds_read_b128 v[80:83], v216
	ds_read_b128 v[84:87], v216 offset:1024
	ds_read_b128 v[104:107], v216 offset:2048
	ds_read_b128 v[108:111], v216 offset:3072
	ds_read_b128 v[128:131], v217
	ds_read_b128 v[132:135], v217 offset:1024
	ds_read_b128 v[152:155], v217 offset:2048
	ds_read_b128 v[156:159], v217 offset:3072
	s_add_u32 s46, s44, 0xfffc0080
	s_addc_u32 s47, s45, -1
	s_cmp_eq_u32 s95, 12
	s_cselect_b32 s49, s23, s47
	s_cselect_b32 s48, s43, s46
	s_cselect_b32 s47, s37, s94
	s_cselect_b32 s46, s92, s93
	v_lshl_add_u64 v[224:225], s[44:45], 0, v[194:195]
	s_add_i32 m0, s53, 0xc000
	ds_read_b128 v[160:163], v218
	ds_read_b128 v[164:167], v218 offset:1024
	ds_read_b128 v[168:171], v218 offset:2048
	ds_read_b128 v[172:175], v218 offset:3072
	ds_read_b128 v[176:179], v218 offset:4096
	ds_read_b128 v[180:183], v218 offset:5120
	ds_read_b128 v[208:211], v218 offset:6144
	ds_read_b128 v[220:223], v218 offset:7168
	global_load_lds_dwordx4 v[224:225], off
	v_lshl_add_u64 v[224:225], s[44:45], 0, v[196:197]
	s_add_i32 m0, s53, 0xe000
	s_nop 0
	global_load_lds_dwordx4 v[224:225], off
	s_waitcnt vmcnt(8)
	s_waitcnt lgkmcnt(0)
	s_barrier
	s_setprio 1
	s_waitcnt lgkmcnt(0)
	v_mfma_f32_16x16x32_bf16 v[148:151], v[80:83], v[160:163], 0
	v_mfma_f32_16x16x32_bf16 v[144:147], v[104:107], v[160:163], 0
	v_mfma_f32_16x16x32_bf16 v[124:127], v[80:83], v[168:171], 0
	v_mfma_f32_16x16x32_bf16 v[120:123], v[104:107], v[168:171], 0
	v_mfma_f32_16x16x32_bf16 v[100:103], v[80:83], v[176:179], 0
	v_mfma_f32_16x16x32_bf16 v[96:99], v[104:107], v[176:179], 0
	v_mfma_f32_16x16x32_bf16 v[76:79], v[80:83], v[208:211], 0
	v_mfma_f32_16x16x32_bf16 v[72:75], v[104:107], v[208:211], 0
	v_mfma_f32_16x16x32_bf16 v[148:151], v[84:87], v[164:167], v[148:151]
	v_mfma_f32_16x16x32_bf16 v[144:147], v[108:111], v[164:167], v[144:147]
	v_mfma_f32_16x16x32_bf16 v[124:127], v[84:87], v[172:175], v[124:127]
	v_mfma_f32_16x16x32_bf16 v[120:123], v[108:111], v[172:175], v[120:123]
	v_mfma_f32_16x16x32_bf16 v[100:103], v[84:87], v[180:183], v[100:103]
	v_mfma_f32_16x16x32_bf16 v[96:99], v[108:111], v[180:183], v[96:99]
	v_mfma_f32_16x16x32_bf16 v[76:79], v[84:87], v[220:223], v[76:79]
	v_mfma_f32_16x16x32_bf16 v[72:75], v[108:111], v[220:223], v[72:75]
	s_setprio 0
	s_setprio 1
	v_mfma_f32_16x16x32_bf16 v[140:143], v[128:131], v[160:163], 0
	v_mfma_f32_16x16x32_bf16 v[136:139], v[152:155], v[160:163], 0
	v_mfma_f32_16x16x32_bf16 v[116:119], v[128:131], v[168:171], 0
	v_mfma_f32_16x16x32_bf16 v[112:115], v[152:155], v[168:171], 0
	v_mfma_f32_16x16x32_bf16 v[92:95], v[128:131], v[176:179], 0
	v_mfma_f32_16x16x32_bf16 v[88:91], v[152:155], v[176:179], 0
	v_mfma_f32_16x16x32_bf16 v[68:71], v[128:131], v[208:211], 0
	v_mfma_f32_16x16x32_bf16 v[64:67], v[152:155], v[208:211], 0
	v_mfma_f32_16x16x32_bf16 v[140:143], v[132:135], v[164:167], v[140:143]
	v_mfma_f32_16x16x32_bf16 v[136:139], v[156:159], v[164:167], v[136:139]
	v_mfma_f32_16x16x32_bf16 v[116:119], v[132:135], v[172:175], v[116:119]
	v_mfma_f32_16x16x32_bf16 v[112:115], v[156:159], v[172:175], v[112:115]
	v_mfma_f32_16x16x32_bf16 v[92:95], v[132:135], v[180:183], v[92:95]
	v_mfma_f32_16x16x32_bf16 v[88:91], v[156:159], v[180:183], v[88:91]
	v_mfma_f32_16x16x32_bf16 v[68:71], v[132:135], v[220:223], v[68:71]
	v_mfma_f32_16x16x32_bf16 v[64:67], v[156:159], v[220:223], v[64:67]
	s_setprio 0
	s_barrier
	s_add_i32 s83, s78, s52
	v_lshl_add_u64 v[224:225], s[46:47], 0, v[186:187]
	s_mov_b32 m0, s83
	ds_read_b128 v[160:163], v218 offset:16384
	ds_read_b128 v[164:167], v218 offset:17408
	ds_read_b128 v[168:171], v218 offset:18432
	ds_read_b128 v[172:175], v218 offset:19456
	ds_read_b128 v[176:179], v218 offset:20480
	ds_read_b128 v[180:183], v218 offset:21504
	ds_read_b128 v[208:211], v218 offset:22528
	ds_read_b128 v[220:223], v218 offset:23552
	global_load_lds_dwordx4 v[224:225], off
	s_add_i32 m0, s83, 0x2000
	s_add_u32 s96, s46, 0x40000
	v_lshl_add_u64 v[226:227], s[46:47], 0, v[190:191]
	s_addc_u32 s97, s47, 0
	s_add_i32 s83, s79, s52
	global_load_lds_dwordx4 v[226:227], off
	v_lshl_add_u64 v[230:231], s[96:97], 0, v[186:187]
	s_mov_b32 m0, s83
	v_lshl_add_u64 v[232:233], s[48:49], 0, v[188:189]
	global_load_lds_dwordx4 v[230:231], off
	v_lshl_add_u64 v[230:231], s[96:97], 0, v[190:191]
	s_add_i32 m0, s83, 0x2000
	s_nop 0
	global_load_lds_dwordx4 v[230:231], off
	v_lshl_add_u64 v[230:231], s[48:49], 0, v[184:185]
	s_mov_b32 m0, s53
	s_nop 0
	global_load_lds_dwordx4 v[230:231], off
	s_mov_b32 m0, s54
	s_nop 0
	global_load_lds_dwordx4 v[232:233], off
	s_waitcnt vmcnt(8)
	s_waitcnt lgkmcnt(0)
	s_barrier
	s_setprio 1
	s_waitcnt lgkmcnt(0)
	v_mfma_f32_16x16x32_bf16 v[60:63], v[80:83], v[160:163], 0
	v_mfma_f32_16x16x32_bf16 v[56:59], v[104:107], v[160:163], 0
	v_mfma_f32_16x16x32_bf16 v[44:47], v[80:83], v[168:171], 0
	v_mfma_f32_16x16x32_bf16 v[40:43], v[104:107], v[168:171], 0
	v_mfma_f32_16x16x32_bf16 v[28:31], v[80:83], v[176:179], 0
	v_mfma_f32_16x16x32_bf16 v[24:27], v[104:107], v[176:179], 0
	v_mfma_f32_16x16x32_bf16 v[12:15], v[80:83], v[208:211], 0
	v_mfma_f32_16x16x32_bf16 v[8:11], v[104:107], v[208:211], 0
	v_mfma_f32_16x16x32_bf16 v[60:63], v[84:87], v[164:167], v[60:63]
	v_mfma_f32_16x16x32_bf16 v[56:59], v[108:111], v[164:167], v[56:59]
	v_mfma_f32_16x16x32_bf16 v[44:47], v[84:87], v[172:175], v[44:47]
	v_mfma_f32_16x16x32_bf16 v[40:43], v[108:111], v[172:175], v[40:43]
	v_mfma_f32_16x16x32_bf16 v[28:31], v[84:87], v[180:183], v[28:31]
	v_mfma_f32_16x16x32_bf16 v[24:27], v[108:111], v[180:183], v[24:27]
	v_mfma_f32_16x16x32_bf16 v[12:15], v[84:87], v[220:223], v[12:15]
	v_mfma_f32_16x16x32_bf16 v[8:11], v[108:111], v[220:223], v[8:11]
	s_setprio 0
	s_setprio 1
	v_mfma_f32_16x16x32_bf16 v[52:55], v[128:131], v[160:163], 0
	v_mfma_f32_16x16x32_bf16 v[48:51], v[152:155], v[160:163], 0
	v_mfma_f32_16x16x32_bf16 v[36:39], v[128:131], v[168:171], 0
	v_mfma_f32_16x16x32_bf16 v[32:35], v[152:155], v[168:171], 0
	v_mfma_f32_16x16x32_bf16 v[20:23], v[128:131], v[176:179], 0
	v_mfma_f32_16x16x32_bf16 v[16:19], v[152:155], v[176:179], 0
	v_mfma_f32_16x16x32_bf16 v[4:7], v[128:131], v[208:211], 0
	v_mfma_f32_16x16x32_bf16 v[0:3], v[152:155], v[208:211], 0
	v_mfma_f32_16x16x32_bf16 v[52:55], v[132:135], v[164:167], v[52:55]
	v_mfma_f32_16x16x32_bf16 v[48:51], v[156:159], v[164:167], v[48:51]
	v_mfma_f32_16x16x32_bf16 v[36:39], v[132:135], v[172:175], v[36:39]
	v_mfma_f32_16x16x32_bf16 v[32:35], v[156:159], v[172:175], v[32:35]
	v_mfma_f32_16x16x32_bf16 v[20:23], v[132:135], v[180:183], v[20:23]
	v_mfma_f32_16x16x32_bf16 v[16:19], v[156:159], v[180:183], v[16:19]
	v_mfma_f32_16x16x32_bf16 v[4:7], v[132:135], v[220:223], v[4:7]
	v_mfma_f32_16x16x32_bf16 v[0:3], v[156:159], v[220:223], v[0:3]
	s_setprio 0
	s_barrier
	s_add_i32 s83, 0, 0x18000
	s_add_i32 s96, 0, 0x1c000
	v_add_u32_e32 v108, s83, v213
	v_add_u32_e32 v156, s96, v213
	ds_read_b128 v[80:83], v108
	ds_read_b128 v[84:87], v108 offset:1024
	ds_read_b128 v[104:107], v108 offset:2048
	ds_read_b128 v[108:111], v108 offset:3072
	ds_read_b128 v[128:131], v156
	ds_read_b128 v[132:135], v156 offset:1024
	ds_read_b128 v[152:155], v156 offset:2048
	ds_read_b128 v[156:159], v156 offset:3072
	s_add_u32 s48, s48, 0x40000
	s_addc_u32 s49, s49, 0
	s_mov_b32 m0, s55
	v_lshl_add_u64 v[234:235], s[48:49], 0, v[184:185]
	ds_read_b128 v[160:163], v218 offset:32768
	ds_read_b128 v[164:167], v218 offset:33792
	ds_read_b128 v[168:171], v218 offset:34816
	ds_read_b128 v[172:175], v218 offset:35840
	ds_read_b128 v[176:179], v218 offset:36864
	ds_read_b128 v[180:183], v218 offset:37888
	ds_read_b128 v[208:211], v218 offset:38912
	ds_read_b128 v[220:223], v218 offset:39936
	global_load_lds_dwordx4 v[234:235], off
	v_lshl_add_u64 v[234:235], s[48:49], 0, v[188:189]
	s_mov_b32 m0, s56
	s_nop 0
	global_load_lds_dwordx4 v[234:235], off
	s_waitcnt vmcnt(8)
	s_waitcnt lgkmcnt(0)
	s_barrier
	s_setprio 1
	s_waitcnt lgkmcnt(0)
	v_mfma_f32_16x16x32_bf16 v[148:151], v[80:83], v[160:163], v[148:151]
	v_mfma_f32_16x16x32_bf16 v[144:147], v[104:107], v[160:163], v[144:147]
	v_mfma_f32_16x16x32_bf16 v[124:127], v[80:83], v[168:171], v[124:127]
	v_mfma_f32_16x16x32_bf16 v[120:123], v[104:107], v[168:171], v[120:123]
	v_mfma_f32_16x16x32_bf16 v[100:103], v[80:83], v[176:179], v[100:103]
	v_mfma_f32_16x16x32_bf16 v[96:99], v[104:107], v[176:179], v[96:99]
	v_mfma_f32_16x16x32_bf16 v[76:79], v[80:83], v[208:211], v[76:79]
	v_mfma_f32_16x16x32_bf16 v[72:75], v[104:107], v[208:211], v[72:75]
	v_mfma_f32_16x16x32_bf16 v[148:151], v[84:87], v[164:167], v[148:151]
	v_mfma_f32_16x16x32_bf16 v[144:147], v[108:111], v[164:167], v[144:147]
	v_mfma_f32_16x16x32_bf16 v[124:127], v[84:87], v[172:175], v[124:127]
	v_mfma_f32_16x16x32_bf16 v[120:123], v[108:111], v[172:175], v[120:123]
	v_mfma_f32_16x16x32_bf16 v[100:103], v[84:87], v[180:183], v[100:103]
	v_mfma_f32_16x16x32_bf16 v[96:99], v[108:111], v[180:183], v[96:99]
	v_mfma_f32_16x16x32_bf16 v[76:79], v[84:87], v[220:223], v[76:79]
	v_mfma_f32_16x16x32_bf16 v[72:75], v[108:111], v[220:223], v[72:75]
	s_setprio 0
	s_setprio 1
	v_mfma_f32_16x16x32_bf16 v[140:143], v[128:131], v[160:163], v[140:143]
	v_mfma_f32_16x16x32_bf16 v[136:139], v[152:155], v[160:163], v[136:139]
	v_mfma_f32_16x16x32_bf16 v[116:119], v[128:131], v[168:171], v[116:119]
	v_mfma_f32_16x16x32_bf16 v[112:115], v[152:155], v[168:171], v[112:115]
	v_mfma_f32_16x16x32_bf16 v[92:95], v[128:131], v[176:179], v[92:95]
	v_mfma_f32_16x16x32_bf16 v[88:91], v[152:155], v[176:179], v[88:91]
	v_mfma_f32_16x16x32_bf16 v[68:71], v[128:131], v[208:211], v[68:71]
	v_mfma_f32_16x16x32_bf16 v[64:67], v[152:155], v[208:211], v[64:67]
	v_mfma_f32_16x16x32_bf16 v[140:143], v[132:135], v[164:167], v[140:143]
	v_mfma_f32_16x16x32_bf16 v[136:139], v[156:159], v[164:167], v[136:139]
	v_mfma_f32_16x16x32_bf16 v[116:119], v[132:135], v[172:175], v[116:119]
	v_mfma_f32_16x16x32_bf16 v[112:115], v[156:159], v[172:175], v[112:115]
	v_mfma_f32_16x16x32_bf16 v[92:95], v[132:135], v[180:183], v[92:95]
	v_mfma_f32_16x16x32_bf16 v[88:91], v[156:159], v[180:183], v[88:91]
	v_mfma_f32_16x16x32_bf16 v[68:71], v[132:135], v[220:223], v[68:71]
	v_mfma_f32_16x16x32_bf16 v[64:67], v[156:159], v[220:223], v[64:67]
	s_setprio 0
	s_barrier
	s_add_i32 s48, s83, s52
	v_lshl_add_u64 v[224:225], v[224:225], 0, s[18:19]
	s_mov_b32 m0, s48
	ds_read_b128 v[160:163], v218 offset:49152
	ds_read_b128 v[164:167], v218 offset:50176
	ds_read_b128 v[168:171], v218 offset:51200
	ds_read_b128 v[172:175], v218 offset:52224
	ds_read_b128 v[176:179], v218 offset:53248
	ds_read_b128 v[180:183], v218 offset:54272
	ds_read_b128 v[208:211], v218 offset:55296
	ds_read_b128 v[220:223], v218 offset:56320
	global_load_lds_dwordx4 v[224:225], off
	s_add_i32 m0, s48, 0x2000
	s_add_u32 s46, s46, 0x40080
	v_lshl_add_u64 v[224:225], v[226:227], 0, s[18:19]
	s_addc_u32 s47, s47, 0
	s_add_i32 s48, s96, s52
	global_load_lds_dwordx4 v[224:225], off
	v_lshl_add_u64 v[224:225], s[46:47], 0, v[186:187]
	s_mov_b32 m0, s48
	s_nop 0
	global_load_lds_dwordx4 v[224:225], off
	v_lshl_add_u64 v[224:225], s[46:47], 0, v[190:191]
	s_add_i32 m0, s48, 0x2000
	s_nop 0
	global_load_lds_dwordx4 v[224:225], off
	v_lshl_add_u64 v[224:225], v[230:231], 0, s[18:19]
	s_mov_b32 m0, s68
	s_nop 0
	global_load_lds_dwordx4 v[224:225], off
	v_lshl_add_u64 v[224:225], v[232:233], 0, s[18:19]
	s_mov_b32 m0, s69
	s_nop 0
	global_load_lds_dwordx4 v[224:225], off
	s_waitcnt vmcnt(8)
	s_waitcnt lgkmcnt(0)
	s_barrier
	s_setprio 1
	s_waitcnt lgkmcnt(0)
	v_mfma_f32_16x16x32_bf16 v[60:63], v[80:83], v[160:163], v[60:63]
	v_mfma_f32_16x16x32_bf16 v[56:59], v[104:107], v[160:163], v[56:59]
	v_mfma_f32_16x16x32_bf16 v[44:47], v[80:83], v[168:171], v[44:47]
	v_mfma_f32_16x16x32_bf16 v[40:43], v[104:107], v[168:171], v[40:43]
	v_mfma_f32_16x16x32_bf16 v[28:31], v[80:83], v[176:179], v[28:31]
	v_mfma_f32_16x16x32_bf16 v[24:27], v[104:107], v[176:179], v[24:27]
	v_mfma_f32_16x16x32_bf16 v[12:15], v[80:83], v[208:211], v[12:15]
	v_mfma_f32_16x16x32_bf16 v[8:11], v[104:107], v[208:211], v[8:11]
	v_mfma_f32_16x16x32_bf16 v[60:63], v[84:87], v[164:167], v[60:63]
	v_mfma_f32_16x16x32_bf16 v[56:59], v[108:111], v[164:167], v[56:59]
	v_mfma_f32_16x16x32_bf16 v[44:47], v[84:87], v[172:175], v[44:47]
	v_mfma_f32_16x16x32_bf16 v[40:43], v[108:111], v[172:175], v[40:43]
	v_mfma_f32_16x16x32_bf16 v[28:31], v[84:87], v[180:183], v[28:31]
	v_mfma_f32_16x16x32_bf16 v[24:27], v[108:111], v[180:183], v[24:27]
	v_mfma_f32_16x16x32_bf16 v[12:15], v[84:87], v[220:223], v[12:15]
	v_mfma_f32_16x16x32_bf16 v[8:11], v[108:111], v[220:223], v[8:11]
	s_setprio 0
	s_setprio 1
	v_mfma_f32_16x16x32_bf16 v[52:55], v[128:131], v[160:163], v[52:55]
	v_mfma_f32_16x16x32_bf16 v[48:51], v[152:155], v[160:163], v[48:51]
	v_mfma_f32_16x16x32_bf16 v[36:39], v[128:131], v[168:171], v[36:39]
	v_mfma_f32_16x16x32_bf16 v[32:35], v[152:155], v[168:171], v[32:35]
	v_mfma_f32_16x16x32_bf16 v[20:23], v[128:131], v[176:179], v[20:23]
	v_mfma_f32_16x16x32_bf16 v[16:19], v[152:155], v[176:179], v[16:19]
	v_mfma_f32_16x16x32_bf16 v[4:7], v[128:131], v[208:211], v[4:7]
	v_mfma_f32_16x16x32_bf16 v[0:3], v[152:155], v[208:211], v[0:3]
	v_mfma_f32_16x16x32_bf16 v[52:55], v[132:135], v[164:167], v[52:55]
	v_mfma_f32_16x16x32_bf16 v[48:51], v[156:159], v[164:167], v[48:51]
	v_mfma_f32_16x16x32_bf16 v[36:39], v[132:135], v[172:175], v[36:39]
	v_mfma_f32_16x16x32_bf16 v[32:35], v[156:159], v[172:175], v[32:35]
	v_mfma_f32_16x16x32_bf16 v[20:23], v[132:135], v[180:183], v[20:23]
	v_mfma_f32_16x16x32_bf16 v[16:19], v[156:159], v[180:183], v[16:19]
	v_mfma_f32_16x16x32_bf16 v[4:7], v[132:135], v[220:223], v[4:7]
	v_mfma_f32_16x16x32_bf16 v[0:3], v[156:159], v[220:223], v[0:3]
	s_setprio 0
	s_barrier
	s_add_i32 s95, s95, 2
	s_add_u32 s44, s44, 0x100
	s_addc_u32 s45, s45, 0
	s_add_u32 s93, s93, 0x100
	s_addc_u32 s94, s94, 0
	s_cmp_gt_u32 s95, 13

.LBB0_758:
	s_ashr_i32 s19, s18, 31
	s_lshl_b64 s[20:21], s[18:19], 19
	s_add_u32 s20, s62, s20
	s_addc_u32 s21, s63, s21
	s_and_b64 s[22:23], s[4:5], exec
	s_cselect_b32 s19, s21, s39
	s_cselect_b32 s57, s20, s38
	s_ashr_i32 s11, s10, 31
	s_lshl_b64 s[22:23], s[10:11], 19
	s_add_u32 s22, s40, s22
	s_addc_u32 s23, s41, s23
	s_and_b64 s[4:5], s[4:5], exec
	s_cselect_b32 s11, s23, s37
	s_cselect_b32 s58, s22, s36
	s_add_u32 s4, s38, 0x40080
	s_addc_u32 s5, s39, 0
	s_add_u32 s59, s36, 0x100
	s_addc_u32 s66, s37, 0
	s_mov_b32 s67, -2
	ds_read_b128 v[146:149], v172
	ds_read_b128 v[166:169], v172 offset:1024
	ds_read_b128 v[176:179], v172 offset:2048
	ds_read_b128 v[180:183], v172 offset:3072
	ds_read_b128 v[184:187], v173
	ds_read_b128 v[188:191], v173 offset:1024
	ds_read_b128 v[192:195], v173 offset:2048
	ds_read_b128 v[196:199], v173 offset:3072
	s_add_u32 s36, s4, 0xfffc0080
	s_addc_u32 s37, s5, -1
	s_cmp_eq_u32 s67, 12
	s_cselect_b32 s39, s19, s37
	s_cselect_b32 s38, s57, s36
	s_cselect_b32 s37, s11, s66
	s_cselect_b32 s36, s58, s59
	v_lshl_add_u64 v[150:151], s[4:5], 0, v[138:139]
	s_add_i32 m0, s27, 0xc000
	ds_read_b128 v[200:203], v174
	ds_read_b128 v[204:207], v174 offset:1024
	ds_read_b128 v[208:211], v174 offset:2048
	ds_read_b128 v[212:215], v174 offset:3072
	ds_read_b128 v[216:219], v174 offset:4096
	ds_read_b128 v[220:223], v174 offset:5120
	ds_read_b128 v[224:227], v174 offset:6144
	ds_read_b128 v[230:233], v174 offset:7168
	global_load_lds_dwordx4 v[150:151], off
	v_lshl_add_u64 v[150:151], s[4:5], 0, v[140:141]
	s_add_i32 m0, s27, 0xe000
	s_nop 0
	global_load_lds_dwordx4 v[150:151], off
	s_waitcnt vmcnt(8)
	s_waitcnt lgkmcnt(0)
	s_barrier
	s_setprio 1
	s_waitcnt lgkmcnt(0)
	v_mfma_f32_16x16x32_bf16 v[124:127], v[146:149], v[200:203], 0
	v_mfma_f32_16x16x32_bf16 v[120:123], v[176:179], v[200:203], 0
	v_mfma_f32_16x16x32_bf16 v[108:111], v[146:149], v[208:211], 0
	v_mfma_f32_16x16x32_bf16 v[104:107], v[176:179], v[208:211], 0
	v_mfma_f32_16x16x32_bf16 v[92:95], v[146:149], v[216:219], 0
	v_mfma_f32_16x16x32_bf16 v[88:91], v[176:179], v[216:219], 0
	v_mfma_f32_16x16x32_bf16 v[76:79], v[146:149], v[224:227], 0
	v_mfma_f32_16x16x32_bf16 v[72:75], v[176:179], v[224:227], 0
	v_mfma_f32_16x16x32_bf16 v[124:127], v[166:169], v[204:207], v[124:127]
	v_mfma_f32_16x16x32_bf16 v[120:123], v[180:183], v[204:207], v[120:123]
	v_mfma_f32_16x16x32_bf16 v[108:111], v[166:169], v[212:215], v[108:111]
	v_mfma_f32_16x16x32_bf16 v[104:107], v[180:183], v[212:215], v[104:107]
	v_mfma_f32_16x16x32_bf16 v[92:95], v[166:169], v[220:223], v[92:95]
	v_mfma_f32_16x16x32_bf16 v[88:91], v[180:183], v[220:223], v[88:91]
	v_mfma_f32_16x16x32_bf16 v[76:79], v[166:169], v[230:233], v[76:79]
	v_mfma_f32_16x16x32_bf16 v[72:75], v[180:183], v[230:233], v[72:75]
	s_setprio 0
	s_setprio 1
	v_mfma_f32_16x16x32_bf16 v[116:119], v[184:187], v[200:203], 0
	v_mfma_f32_16x16x32_bf16 v[112:115], v[192:195], v[200:203], 0
	v_mfma_f32_16x16x32_bf16 v[100:103], v[184:187], v[208:211], 0
	v_mfma_f32_16x16x32_bf16 v[96:99], v[192:195], v[208:211], 0
	v_mfma_f32_16x16x32_bf16 v[84:87], v[184:187], v[216:219], 0
	v_mfma_f32_16x16x32_bf16 v[80:83], v[192:195], v[216:219], 0
	v_mfma_f32_16x16x32_bf16 v[68:71], v[184:187], v[224:227], 0
	v_mfma_f32_16x16x32_bf16 v[64:67], v[192:195], v[224:227], 0
	v_mfma_f32_16x16x32_bf16 v[116:119], v[188:191], v[204:207], v[116:119]
	v_mfma_f32_16x16x32_bf16 v[112:115], v[196:199], v[204:207], v[112:115]
	v_mfma_f32_16x16x32_bf16 v[100:103], v[188:191], v[212:215], v[100:103]
	v_mfma_f32_16x16x32_bf16 v[96:99], v[196:199], v[212:215], v[96:99]
	v_mfma_f32_16x16x32_bf16 v[84:87], v[188:191], v[220:223], v[84:87]
	v_mfma_f32_16x16x32_bf16 v[80:83], v[196:199], v[220:223], v[80:83]
	v_mfma_f32_16x16x32_bf16 v[68:71], v[188:191], v[230:233], v[68:71]
	v_mfma_f32_16x16x32_bf16 v[64:67], v[196:199], v[230:233], v[64:67]
	s_setprio 0
	s_barrier
	s_add_i32 s68, s53, s42
	v_lshl_add_u64 v[150:151], s[36:37], 0, v[132:133]
	s_mov_b32 m0, s68
	ds_read_b128 v[200:203], v174 offset:16384
	ds_read_b128 v[204:207], v174 offset:17408
	ds_read_b128 v[208:211], v174 offset:18432
	ds_read_b128 v[212:215], v174 offset:19456
	ds_read_b128 v[216:219], v174 offset:20480
	ds_read_b128 v[220:223], v174 offset:21504
	ds_read_b128 v[224:227], v174 offset:22528
	ds_read_b128 v[230:233], v174 offset:23552
	global_load_lds_dwordx4 v[150:151], off
	s_add_i32 m0, s68, 0x2000
	s_add_u32 s68, s36, 0x40000
	v_lshl_add_u64 v[154:155], s[36:37], 0, v[128:129]
	s_addc_u32 s69, s37, 0
	s_add_i32 s70, s54, s42
	global_load_lds_dwordx4 v[154:155], off
	v_lshl_add_u64 v[158:159], s[68:69], 0, v[132:133]
	s_mov_b32 m0, s70
	v_lshl_add_u64 v[162:163], s[38:39], 0, v[130:131]
	global_load_lds_dwordx4 v[158:159], off
	v_lshl_add_u64 v[158:159], s[68:69], 0, v[128:129]
	s_add_i32 m0, s70, 0x2000
	s_nop 0
	global_load_lds_dwordx4 v[158:159], off
	v_lshl_add_u64 v[158:159], s[38:39], 0, v[134:135]
	s_mov_b32 m0, s27
	s_nop 0
	global_load_lds_dwordx4 v[158:159], off
	s_mov_b32 m0, s45
	s_nop 0
	global_load_lds_dwordx4 v[162:163], off
	s_waitcnt vmcnt(8)
	s_waitcnt lgkmcnt(0)
	s_barrier
	s_setprio 1
	s_waitcnt lgkmcnt(0)
	v_mfma_f32_16x16x32_bf16 v[60:63], v[146:149], v[200:203], 0
	v_mfma_f32_16x16x32_bf16 v[56:59], v[176:179], v[200:203], 0
	v_mfma_f32_16x16x32_bf16 v[44:47], v[146:149], v[208:211], 0
	v_mfma_f32_16x16x32_bf16 v[40:43], v[176:179], v[208:211], 0
	v_mfma_f32_16x16x32_bf16 v[28:31], v[146:149], v[216:219], 0
	v_mfma_f32_16x16x32_bf16 v[24:27], v[176:179], v[216:219], 0
	v_mfma_f32_16x16x32_bf16 v[12:15], v[146:149], v[224:227], 0
	v_mfma_f32_16x16x32_bf16 v[8:11], v[176:179], v[224:227], 0
	v_mfma_f32_16x16x32_bf16 v[60:63], v[166:169], v[204:207], v[60:63]
	v_mfma_f32_16x16x32_bf16 v[56:59], v[180:183], v[204:207], v[56:59]
	v_mfma_f32_16x16x32_bf16 v[44:47], v[166:169], v[212:215], v[44:47]
	v_mfma_f32_16x16x32_bf16 v[40:43], v[180:183], v[212:215], v[40:43]
	v_mfma_f32_16x16x32_bf16 v[28:31], v[166:169], v[220:223], v[28:31]
	v_mfma_f32_16x16x32_bf16 v[24:27], v[180:183], v[220:223], v[24:27]
	v_mfma_f32_16x16x32_bf16 v[12:15], v[166:169], v[230:233], v[12:15]
	v_mfma_f32_16x16x32_bf16 v[8:11], v[180:183], v[230:233], v[8:11]
	s_setprio 0
	s_setprio 1
	v_mfma_f32_16x16x32_bf16 v[52:55], v[184:187], v[200:203], 0
	v_mfma_f32_16x16x32_bf16 v[48:51], v[192:195], v[200:203], 0
	v_mfma_f32_16x16x32_bf16 v[36:39], v[184:187], v[208:211], 0
	v_mfma_f32_16x16x32_bf16 v[32:35], v[192:195], v[208:211], 0
	v_mfma_f32_16x16x32_bf16 v[20:23], v[184:187], v[216:219], 0
	v_mfma_f32_16x16x32_bf16 v[16:19], v[192:195], v[216:219], 0
	v_mfma_f32_16x16x32_bf16 v[4:7], v[184:187], v[224:227], 0
	v_mfma_f32_16x16x32_bf16 v[0:3], v[192:195], v[224:227], 0
	v_mfma_f32_16x16x32_bf16 v[52:55], v[188:191], v[204:207], v[52:55]
	v_mfma_f32_16x16x32_bf16 v[48:51], v[196:199], v[204:207], v[48:51]
	v_mfma_f32_16x16x32_bf16 v[36:39], v[188:191], v[212:215], v[36:39]
	v_mfma_f32_16x16x32_bf16 v[32:35], v[196:199], v[212:215], v[32:35]
	v_mfma_f32_16x16x32_bf16 v[20:23], v[188:191], v[220:223], v[20:23]
	v_mfma_f32_16x16x32_bf16 v[16:19], v[196:199], v[220:223], v[16:19]
	v_mfma_f32_16x16x32_bf16 v[4:7], v[188:191], v[230:233], v[4:7]
	v_mfma_f32_16x16x32_bf16 v[0:3], v[196:199], v[230:233], v[0:3]
	s_setprio 0
	s_barrier
	s_add_i32 s68, 0, 0x18000
	v_add_u32_e32 v152, s68, v157
	s_add_i32 s69, 0, 0x1c000
	ds_read_b128 v[146:149], v152
	ds_read_b128 v[166:169], v152 offset:1024
	ds_read_b128 v[176:179], v152 offset:2048
	ds_read_b128 v[180:183], v152 offset:3072
	v_add_u32_e32 v152, s69, v157
	ds_read_b128 v[184:187], v152
	ds_read_b128 v[188:191], v152 offset:1024
	ds_read_b128 v[192:195], v152 offset:2048
	ds_read_b128 v[196:199], v152 offset:3072
	s_add_u32 s38, s38, 0x40000
	s_addc_u32 s39, s39, 0
	s_mov_b32 m0, s46
	v_lshl_add_u64 v[234:235], s[38:39], 0, v[134:135]
	ds_read_b128 v[200:203], v174 offset:32768
	ds_read_b128 v[204:207], v174 offset:33792
	ds_read_b128 v[208:211], v174 offset:34816
	ds_read_b128 v[212:215], v174 offset:35840
	ds_read_b128 v[216:219], v174 offset:36864
	ds_read_b128 v[220:223], v174 offset:37888
	ds_read_b128 v[224:227], v174 offset:38912
	ds_read_b128 v[230:233], v174 offset:39936
	global_load_lds_dwordx4 v[234:235], off
	v_lshl_add_u64 v[234:235], s[38:39], 0, v[130:131]
	s_mov_b32 m0, s47
	s_nop 0
	global_load_lds_dwordx4 v[234:235], off
	s_waitcnt vmcnt(8)
	s_waitcnt lgkmcnt(0)
	s_barrier
	s_setprio 1
	s_waitcnt lgkmcnt(0)
	v_mfma_f32_16x16x32_bf16 v[124:127], v[146:149], v[200:203], v[124:127]
	v_mfma_f32_16x16x32_bf16 v[120:123], v[176:179], v[200:203], v[120:123]
	v_mfma_f32_16x16x32_bf16 v[108:111], v[146:149], v[208:211], v[108:111]
	v_mfma_f32_16x16x32_bf16 v[104:107], v[176:179], v[208:211], v[104:107]
	v_mfma_f32_16x16x32_bf16 v[92:95], v[146:149], v[216:219], v[92:95]
	v_mfma_f32_16x16x32_bf16 v[88:91], v[176:179], v[216:219], v[88:91]
	v_mfma_f32_16x16x32_bf16 v[76:79], v[146:149], v[224:227], v[76:79]
	v_mfma_f32_16x16x32_bf16 v[72:75], v[176:179], v[224:227], v[72:75]
	v_mfma_f32_16x16x32_bf16 v[124:127], v[166:169], v[204:207], v[124:127]
	v_mfma_f32_16x16x32_bf16 v[120:123], v[180:183], v[204:207], v[120:123]
	v_mfma_f32_16x16x32_bf16 v[108:111], v[166:169], v[212:215], v[108:111]
	v_mfma_f32_16x16x32_bf16 v[104:107], v[180:183], v[212:215], v[104:107]
	v_mfma_f32_16x16x32_bf16 v[92:95], v[166:169], v[220:223], v[92:95]
	v_mfma_f32_16x16x32_bf16 v[88:91], v[180:183], v[220:223], v[88:91]
	v_mfma_f32_16x16x32_bf16 v[76:79], v[166:169], v[230:233], v[76:79]
	v_mfma_f32_16x16x32_bf16 v[72:75], v[180:183], v[230:233], v[72:75]
	s_setprio 0
	s_setprio 1
	v_mfma_f32_16x16x32_bf16 v[116:119], v[184:187], v[200:203], v[116:119]
	v_mfma_f32_16x16x32_bf16 v[112:115], v[192:195], v[200:203], v[112:115]
	v_mfma_f32_16x16x32_bf16 v[100:103], v[184:187], v[208:211], v[100:103]
	v_mfma_f32_16x16x32_bf16 v[96:99], v[192:195], v[208:211], v[96:99]
	v_mfma_f32_16x16x32_bf16 v[84:87], v[184:187], v[216:219], v[84:87]
	v_mfma_f32_16x16x32_bf16 v[80:83], v[192:195], v[216:219], v[80:83]
	v_mfma_f32_16x16x32_bf16 v[68:71], v[184:187], v[224:227], v[68:71]
	v_mfma_f32_16x16x32_bf16 v[64:67], v[192:195], v[224:227], v[64:67]
	v_mfma_f32_16x16x32_bf16 v[116:119], v[188:191], v[204:207], v[116:119]
	v_mfma_f32_16x16x32_bf16 v[112:115], v[196:199], v[204:207], v[112:115]
	v_mfma_f32_16x16x32_bf16 v[100:103], v[188:191], v[212:215], v[100:103]
	v_mfma_f32_16x16x32_bf16 v[96:99], v[196:199], v[212:215], v[96:99]
	v_mfma_f32_16x16x32_bf16 v[84:87], v[188:191], v[220:223], v[84:87]
	v_mfma_f32_16x16x32_bf16 v[80:83], v[196:199], v[220:223], v[80:83]
	v_mfma_f32_16x16x32_bf16 v[68:71], v[188:191], v[230:233], v[68:71]
	v_mfma_f32_16x16x32_bf16 v[64:67], v[196:199], v[230:233], v[64:67]
	s_setprio 0
	s_barrier
	s_add_i32 s38, s68, s42
	v_lshl_add_u64 v[150:151], v[150:151], 0, s[14:15]
	s_mov_b32 m0, s38
	ds_read_b128 v[200:203], v174 offset:49152
	ds_read_b128 v[204:207], v174 offset:50176
	ds_read_b128 v[208:211], v174 offset:51200
	ds_read_b128 v[212:215], v174 offset:52224
	ds_read_b128 v[216:219], v174 offset:53248
	ds_read_b128 v[220:223], v174 offset:54272
	ds_read_b128 v[224:227], v174 offset:55296
	ds_read_b128 v[230:233], v174 offset:56320
	global_load_lds_dwordx4 v[150:151], off
	s_add_i32 m0, s38, 0x2000
	s_add_u32 s36, s36, 0x40080
	v_lshl_add_u64 v[150:151], v[154:155], 0, s[14:15]
	s_addc_u32 s37, s37, 0
	s_add_i32 s38, s69, s42
	global_load_lds_dwordx4 v[150:151], off
	v_lshl_add_u64 v[150:151], s[36:37], 0, v[132:133]
	s_mov_b32 m0, s38
	s_nop 0
	global_load_lds_dwordx4 v[150:151], off
	v_lshl_add_u64 v[150:151], s[36:37], 0, v[128:129]
	s_add_i32 m0, s38, 0x2000
	s_nop 0
	global_load_lds_dwordx4 v[150:151], off
	v_lshl_add_u64 v[150:151], v[158:159], 0, s[14:15]
	s_mov_b32 m0, s49
	s_nop 0
	global_load_lds_dwordx4 v[150:151], off
	v_lshl_add_u64 v[150:151], v[162:163], 0, s[14:15]
	s_mov_b32 m0, s50
	s_nop 0
	global_load_lds_dwordx4 v[150:151], off
	s_waitcnt vmcnt(8)
	s_waitcnt lgkmcnt(0)
	s_barrier
	s_setprio 1
	s_waitcnt lgkmcnt(0)
	v_mfma_f32_16x16x32_bf16 v[60:63], v[146:149], v[200:203], v[60:63]
	v_mfma_f32_16x16x32_bf16 v[56:59], v[176:179], v[200:203], v[56:59]
	v_mfma_f32_16x16x32_bf16 v[44:47], v[146:149], v[208:211], v[44:47]
	v_mfma_f32_16x16x32_bf16 v[40:43], v[176:179], v[208:211], v[40:43]
	v_mfma_f32_16x16x32_bf16 v[28:31], v[146:149], v[216:219], v[28:31]
	v_mfma_f32_16x16x32_bf16 v[24:27], v[176:179], v[216:219], v[24:27]
	v_mfma_f32_16x16x32_bf16 v[12:15], v[146:149], v[224:227], v[12:15]
	v_mfma_f32_16x16x32_bf16 v[8:11], v[176:179], v[224:227], v[8:11]
	v_mfma_f32_16x16x32_bf16 v[60:63], v[166:169], v[204:207], v[60:63]
	v_mfma_f32_16x16x32_bf16 v[56:59], v[180:183], v[204:207], v[56:59]
	v_mfma_f32_16x16x32_bf16 v[44:47], v[166:169], v[212:215], v[44:47]
	v_mfma_f32_16x16x32_bf16 v[40:43], v[180:183], v[212:215], v[40:43]
	v_mfma_f32_16x16x32_bf16 v[28:31], v[166:169], v[220:223], v[28:31]
	v_mfma_f32_16x16x32_bf16 v[24:27], v[180:183], v[220:223], v[24:27]
	v_mfma_f32_16x16x32_bf16 v[12:15], v[166:169], v[230:233], v[12:15]
	v_mfma_f32_16x16x32_bf16 v[8:11], v[180:183], v[230:233], v[8:11]
	s_setprio 0
	s_setprio 1
	v_mfma_f32_16x16x32_bf16 v[52:55], v[184:187], v[200:203], v[52:55]
	v_mfma_f32_16x16x32_bf16 v[48:51], v[192:195], v[200:203], v[48:51]
	v_mfma_f32_16x16x32_bf16 v[36:39], v[184:187], v[208:211], v[36:39]
	v_mfma_f32_16x16x32_bf16 v[32:35], v[192:195], v[208:211], v[32:35]
	v_mfma_f32_16x16x32_bf16 v[20:23], v[184:187], v[216:219], v[20:23]
	v_mfma_f32_16x16x32_bf16 v[16:19], v[192:195], v[216:219], v[16:19]
	v_mfma_f32_16x16x32_bf16 v[4:7], v[184:187], v[224:227], v[4:7]
	v_mfma_f32_16x16x32_bf16 v[0:3], v[192:195], v[224:227], v[0:3]
	v_mfma_f32_16x16x32_bf16 v[52:55], v[188:191], v[204:207], v[52:55]
	v_mfma_f32_16x16x32_bf16 v[48:51], v[196:199], v[204:207], v[48:51]
	v_mfma_f32_16x16x32_bf16 v[36:39], v[188:191], v[212:215], v[36:39]
	v_mfma_f32_16x16x32_bf16 v[32:35], v[196:199], v[212:215], v[32:35]
	v_mfma_f32_16x16x32_bf16 v[20:23], v[188:191], v[220:223], v[20:23]
	v_mfma_f32_16x16x32_bf16 v[16:19], v[196:199], v[220:223], v[16:19]
	v_mfma_f32_16x16x32_bf16 v[4:7], v[188:191], v[230:233], v[4:7]
	v_mfma_f32_16x16x32_bf16 v[0:3], v[196:199], v[230:233], v[0:3]
	s_setprio 0
	s_barrier
	s_add_i32 s67, s67, 2
	s_add_u32 s4, s4, 0x100
	s_addc_u32 s5, s5, 0
	s_add_u32 s59, s59, 0x100
	s_addc_u32 s66, s66, 0
	s_cmp_gt_u32 s67, 13

.LBB0_835:
	s_add_u32 s80, s22, 0x100
	s_addc_u32 s81, s23, 0
	s_mov_b32 s82, -2
	ds_read_b128 v[112:115], v203
	ds_read_b128 v[116:119], v203 offset:1024
	ds_read_b128 v[136:139], v203 offset:2048
	ds_read_b128 v[140:143], v203 offset:3072
	ds_read_b128 v[144:147], v204
	ds_read_b128 v[148:151], v204 offset:1024
	ds_read_b128 v[152:155], v204 offset:2048
	ds_read_b128 v[156:159], v204 offset:3072
	s_add_u32 s22, s20, 0x100
	s_addc_u32 s23, s21, 0
	s_cmp_eq_u32 s82, 40
	s_cselect_b32 s37, s7, s23
	s_cselect_b32 s36, s6, s22
	s_cselect_b32 s27, s19, s81
	s_cselect_b32 s26, s18, s80
	v_lshl_add_u64 v[200:201], s[20:21], 0, v[186:187]
	s_add_i32 m0, s43, 0xc000
	ds_read_b128 v[160:163], v205
	ds_read_b128 v[164:167], v205 offset:1024
	ds_read_b128 v[168:171], v205 offset:2048
	ds_read_b128 v[172:175], v205 offset:3072
	ds_read_b128 v[206:209], v205 offset:4096
	ds_read_b128 v[210:213], v205 offset:5120
	ds_read_b128 v[214:217], v205 offset:6144
	ds_read_b128 v[218:221], v205 offset:7168
	global_load_lds_dwordx4 v[200:201], off
	v_lshl_add_u64 v[200:201], s[20:21], 0, v[188:189]
	s_add_i32 m0, s43, 0xe000
	s_nop 0
	global_load_lds_dwordx4 v[200:201], off
	s_waitcnt vmcnt(8)
	s_waitcnt lgkmcnt(0)
	s_barrier
	s_setprio 1
	s_waitcnt lgkmcnt(0)
	v_mfma_f32_16x16x32_bf16 v[132:135], v[112:115], v[160:163], 0
	v_mfma_f32_16x16x32_bf16 v[128:131], v[136:139], v[160:163], 0
	v_mfma_f32_16x16x32_bf16 v[108:111], v[112:115], v[168:171], 0
	v_mfma_f32_16x16x32_bf16 v[104:107], v[136:139], v[168:171], 0
	v_mfma_f32_16x16x32_bf16 v[92:95], v[112:115], v[206:209], 0
	v_mfma_f32_16x16x32_bf16 v[88:91], v[136:139], v[206:209], 0
	v_mfma_f32_16x16x32_bf16 v[76:79], v[112:115], v[214:217], 0
	v_mfma_f32_16x16x32_bf16 v[72:75], v[136:139], v[214:217], 0
	v_mfma_f32_16x16x32_bf16 v[132:135], v[116:119], v[164:167], v[132:135]
	v_mfma_f32_16x16x32_bf16 v[128:131], v[140:143], v[164:167], v[128:131]
	v_mfma_f32_16x16x32_bf16 v[108:111], v[116:119], v[172:175], v[108:111]
	v_mfma_f32_16x16x32_bf16 v[104:107], v[140:143], v[172:175], v[104:107]
	v_mfma_f32_16x16x32_bf16 v[92:95], v[116:119], v[210:213], v[92:95]
	v_mfma_f32_16x16x32_bf16 v[88:91], v[140:143], v[210:213], v[88:91]
	v_mfma_f32_16x16x32_bf16 v[76:79], v[116:119], v[218:221], v[76:79]
	v_mfma_f32_16x16x32_bf16 v[72:75], v[140:143], v[218:221], v[72:75]
	s_setprio 0
	s_setprio 1
	v_mfma_f32_16x16x32_bf16 v[124:127], v[144:147], v[160:163], 0
	v_mfma_f32_16x16x32_bf16 v[120:123], v[152:155], v[160:163], 0
	v_mfma_f32_16x16x32_bf16 v[100:103], v[144:147], v[168:171], 0
	v_mfma_f32_16x16x32_bf16 v[96:99], v[152:155], v[168:171], 0
	v_mfma_f32_16x16x32_bf16 v[84:87], v[144:147], v[206:209], 0
	v_mfma_f32_16x16x32_bf16 v[80:83], v[152:155], v[206:209], 0
	v_mfma_f32_16x16x32_bf16 v[68:71], v[144:147], v[214:217], 0
	v_mfma_f32_16x16x32_bf16 v[64:67], v[152:155], v[214:217], 0
	v_mfma_f32_16x16x32_bf16 v[124:127], v[148:151], v[164:167], v[124:127]
	v_mfma_f32_16x16x32_bf16 v[120:123], v[156:159], v[164:167], v[120:123]
	v_mfma_f32_16x16x32_bf16 v[100:103], v[148:151], v[172:175], v[100:103]
	v_mfma_f32_16x16x32_bf16 v[96:99], v[156:159], v[172:175], v[96:99]
	v_mfma_f32_16x16x32_bf16 v[84:87], v[148:151], v[210:213], v[84:87]
	v_mfma_f32_16x16x32_bf16 v[80:83], v[156:159], v[210:213], v[80:83]
	v_mfma_f32_16x16x32_bf16 v[68:71], v[148:151], v[218:221], v[68:71]
	v_mfma_f32_16x16x32_bf16 v[64:67], v[156:159], v[218:221], v[64:67]
	s_setprio 0
	s_barrier
	s_add_i32 s20, s59, s40
	v_lshl_add_u64 v[200:201], s[26:27], 0, v[180:181]
	s_mov_b32 m0, s20
	ds_read_b128 v[160:163], v205 offset:16384
	ds_read_b128 v[164:167], v205 offset:17408
	ds_read_b128 v[168:171], v205 offset:18432
	ds_read_b128 v[172:175], v205 offset:19456
	ds_read_b128 v[206:209], v205 offset:20480
	ds_read_b128 v[210:213], v205 offset:21504
	ds_read_b128 v[214:217], v205 offset:22528
	ds_read_b128 v[218:221], v205 offset:23552
	global_load_lds_dwordx4 v[200:201], off
	s_add_i32 m0, s20, 0x2000
	s_add_u32 s20, s26, 0xb0000
	v_lshl_add_u64 v[222:223], s[26:27], 0, v[176:177]
	s_addc_u32 s21, s27, 0
	s_add_i32 s83, s66, s40
	global_load_lds_dwordx4 v[222:223], off
	v_lshl_add_u64 v[224:225], s[20:21], 0, v[180:181]
	s_mov_b32 m0, s83
	v_lshl_add_u64 v[226:227], s[36:37], 0, v[178:179]
	global_load_lds_dwordx4 v[224:225], off
	v_lshl_add_u64 v[224:225], s[20:21], 0, v[176:177]
	s_add_i32 m0, s83, 0x2000
	s_nop 0
	global_load_lds_dwordx4 v[224:225], off
	v_lshl_add_u64 v[224:225], s[36:37], 0, v[182:183]
	s_mov_b32 m0, s43
	s_nop 0
	global_load_lds_dwordx4 v[224:225], off
	s_mov_b32 m0, s44
	s_nop 0
	global_load_lds_dwordx4 v[226:227], off
	s_waitcnt vmcnt(8)
	s_waitcnt lgkmcnt(0)
	s_barrier
	s_setprio 1
	s_waitcnt lgkmcnt(0)
	v_mfma_f32_16x16x32_bf16 v[60:63], v[112:115], v[160:163], 0
	v_mfma_f32_16x16x32_bf16 v[56:59], v[136:139], v[160:163], 0
	v_mfma_f32_16x16x32_bf16 v[44:47], v[112:115], v[168:171], 0
	v_mfma_f32_16x16x32_bf16 v[40:43], v[136:139], v[168:171], 0
	v_mfma_f32_16x16x32_bf16 v[28:31], v[112:115], v[206:209], 0
	v_mfma_f32_16x16x32_bf16 v[24:27], v[136:139], v[206:209], 0
	v_mfma_f32_16x16x32_bf16 v[12:15], v[112:115], v[214:217], 0
	v_mfma_f32_16x16x32_bf16 v[8:11], v[136:139], v[214:217], 0
	v_mfma_f32_16x16x32_bf16 v[60:63], v[116:119], v[164:167], v[60:63]
	v_mfma_f32_16x16x32_bf16 v[56:59], v[140:143], v[164:167], v[56:59]
	v_mfma_f32_16x16x32_bf16 v[44:47], v[116:119], v[172:175], v[44:47]
	v_mfma_f32_16x16x32_bf16 v[40:43], v[140:143], v[172:175], v[40:43]
	v_mfma_f32_16x16x32_bf16 v[28:31], v[116:119], v[210:213], v[28:31]
	v_mfma_f32_16x16x32_bf16 v[24:27], v[140:143], v[210:213], v[24:27]
	v_mfma_f32_16x16x32_bf16 v[12:15], v[116:119], v[218:221], v[12:15]
	v_mfma_f32_16x16x32_bf16 v[8:11], v[140:143], v[218:221], v[8:11]
	s_setprio 0
	s_setprio 1
	v_mfma_f32_16x16x32_bf16 v[52:55], v[144:147], v[160:163], 0
	v_mfma_f32_16x16x32_bf16 v[48:51], v[152:155], v[160:163], 0
	v_mfma_f32_16x16x32_bf16 v[36:39], v[144:147], v[168:171], 0
	v_mfma_f32_16x16x32_bf16 v[32:35], v[152:155], v[168:171], 0
	v_mfma_f32_16x16x32_bf16 v[20:23], v[144:147], v[206:209], 0
	v_mfma_f32_16x16x32_bf16 v[16:19], v[152:155], v[206:209], 0
	v_mfma_f32_16x16x32_bf16 v[4:7], v[144:147], v[214:217], 0
	v_mfma_f32_16x16x32_bf16 v[0:3], v[152:155], v[214:217], 0
	v_mfma_f32_16x16x32_bf16 v[52:55], v[148:151], v[164:167], v[52:55]
	v_mfma_f32_16x16x32_bf16 v[48:51], v[156:159], v[164:167], v[48:51]
	v_mfma_f32_16x16x32_bf16 v[36:39], v[148:151], v[172:175], v[36:39]
	v_mfma_f32_16x16x32_bf16 v[32:35], v[156:159], v[172:175], v[32:35]
	v_mfma_f32_16x16x32_bf16 v[20:23], v[148:151], v[210:213], v[20:23]
	v_mfma_f32_16x16x32_bf16 v[16:19], v[156:159], v[210:213], v[16:19]
	v_mfma_f32_16x16x32_bf16 v[4:7], v[148:151], v[218:221], v[4:7]
	v_mfma_f32_16x16x32_bf16 v[0:3], v[156:159], v[218:221], v[0:3]
	s_setprio 0
	s_barrier
	s_add_i32 s83, 0, 0x18000
	s_add_i32 s85, 0, 0x1c000
	v_add_u32_e32 v140, s83, v202
	v_add_u32_e32 v156, s85, v202
	ds_read_b128 v[112:115], v140
	ds_read_b128 v[116:119], v140 offset:1024
	ds_read_b128 v[136:139], v140 offset:2048
	ds_read_b128 v[140:143], v140 offset:3072
	ds_read_b128 v[144:147], v156
	ds_read_b128 v[148:151], v156 offset:1024
	ds_read_b128 v[152:155], v156 offset:2048
	ds_read_b128 v[156:159], v156 offset:3072
	s_add_u32 s20, s36, 0xb0000
	s_addc_u32 s21, s37, 0
	s_mov_b32 m0, s45
	v_lshl_add_u64 v[230:231], s[20:21], 0, v[182:183]
	ds_read_b128 v[160:163], v205 offset:32768
	ds_read_b128 v[164:167], v205 offset:33792
	ds_read_b128 v[168:171], v205 offset:34816
	ds_read_b128 v[172:175], v205 offset:35840
	ds_read_b128 v[206:209], v205 offset:36864
	ds_read_b128 v[210:213], v205 offset:37888
	ds_read_b128 v[214:217], v205 offset:38912
	ds_read_b128 v[218:221], v205 offset:39936
	global_load_lds_dwordx4 v[230:231], off
	v_lshl_add_u64 v[230:231], s[20:21], 0, v[178:179]
	s_mov_b32 m0, s46
	s_nop 0
	global_load_lds_dwordx4 v[230:231], off
	s_waitcnt vmcnt(8)
	s_waitcnt lgkmcnt(0)
	s_barrier
	s_setprio 1
	s_waitcnt lgkmcnt(0)
	v_mfma_f32_16x16x32_bf16 v[132:135], v[112:115], v[160:163], v[132:135]
	v_mfma_f32_16x16x32_bf16 v[128:131], v[136:139], v[160:163], v[128:131]
	v_mfma_f32_16x16x32_bf16 v[108:111], v[112:115], v[168:171], v[108:111]
	v_mfma_f32_16x16x32_bf16 v[104:107], v[136:139], v[168:171], v[104:107]
	v_mfma_f32_16x16x32_bf16 v[92:95], v[112:115], v[206:209], v[92:95]
	v_mfma_f32_16x16x32_bf16 v[88:91], v[136:139], v[206:209], v[88:91]
	v_mfma_f32_16x16x32_bf16 v[76:79], v[112:115], v[214:217], v[76:79]
	v_mfma_f32_16x16x32_bf16 v[72:75], v[136:139], v[214:217], v[72:75]
	v_mfma_f32_16x16x32_bf16 v[132:135], v[116:119], v[164:167], v[132:135]
	v_mfma_f32_16x16x32_bf16 v[128:131], v[140:143], v[164:167], v[128:131]
	v_mfma_f32_16x16x32_bf16 v[108:111], v[116:119], v[172:175], v[108:111]
	v_mfma_f32_16x16x32_bf16 v[104:107], v[140:143], v[172:175], v[104:107]
	v_mfma_f32_16x16x32_bf16 v[92:95], v[116:119], v[210:213], v[92:95]
	v_mfma_f32_16x16x32_bf16 v[88:91], v[140:143], v[210:213], v[88:91]
	v_mfma_f32_16x16x32_bf16 v[76:79], v[116:119], v[218:221], v[76:79]
	v_mfma_f32_16x16x32_bf16 v[72:75], v[140:143], v[218:221], v[72:75]
	s_setprio 0
	s_setprio 1
	v_mfma_f32_16x16x32_bf16 v[124:127], v[144:147], v[160:163], v[124:127]
	v_mfma_f32_16x16x32_bf16 v[120:123], v[152:155], v[160:163], v[120:123]
	v_mfma_f32_16x16x32_bf16 v[100:103], v[144:147], v[168:171], v[100:103]
	v_mfma_f32_16x16x32_bf16 v[96:99], v[152:155], v[168:171], v[96:99]
	v_mfma_f32_16x16x32_bf16 v[84:87], v[144:147], v[206:209], v[84:87]
	v_mfma_f32_16x16x32_bf16 v[80:83], v[152:155], v[206:209], v[80:83]
	v_mfma_f32_16x16x32_bf16 v[68:71], v[144:147], v[214:217], v[68:71]
	v_mfma_f32_16x16x32_bf16 v[64:67], v[152:155], v[214:217], v[64:67]
	v_mfma_f32_16x16x32_bf16 v[124:127], v[148:151], v[164:167], v[124:127]
	v_mfma_f32_16x16x32_bf16 v[120:123], v[156:159], v[164:167], v[120:123]
	v_mfma_f32_16x16x32_bf16 v[100:103], v[148:151], v[172:175], v[100:103]
	v_mfma_f32_16x16x32_bf16 v[96:99], v[156:159], v[172:175], v[96:99]
	v_mfma_f32_16x16x32_bf16 v[84:87], v[148:151], v[210:213], v[84:87]
	v_mfma_f32_16x16x32_bf16 v[80:83], v[156:159], v[210:213], v[80:83]
	v_mfma_f32_16x16x32_bf16 v[68:71], v[148:151], v[218:221], v[68:71]
	v_mfma_f32_16x16x32_bf16 v[64:67], v[156:159], v[218:221], v[64:67]
	s_setprio 0
	s_barrier
	s_add_i32 s20, s83, s40
	v_lshl_add_u64 v[200:201], v[200:201], 0, s[14:15]
	s_mov_b32 m0, s20
	ds_read_b128 v[160:163], v205 offset:49152
	ds_read_b128 v[164:167], v205 offset:50176
	ds_read_b128 v[168:171], v205 offset:51200
	ds_read_b128 v[172:175], v205 offset:52224
	ds_read_b128 v[206:209], v205 offset:53248
	ds_read_b128 v[210:213], v205 offset:54272
	ds_read_b128 v[214:217], v205 offset:55296
	ds_read_b128 v[218:221], v205 offset:56320
	global_load_lds_dwordx4 v[200:201], off
	s_add_i32 m0, s20, 0x2000
	s_add_u32 s20, s26, 0xb0080
	v_lshl_add_u64 v[200:201], v[222:223], 0, s[14:15]
	s_addc_u32 s21, s27, 0
	s_add_i32 s26, s85, s40
	global_load_lds_dwordx4 v[200:201], off
	v_lshl_add_u64 v[200:201], s[20:21], 0, v[180:181]
	s_mov_b32 m0, s26
	s_nop 0
	global_load_lds_dwordx4 v[200:201], off
	v_lshl_add_u64 v[200:201], s[20:21], 0, v[176:177]
	s_add_i32 m0, s26, 0x2000
	s_nop 0
	global_load_lds_dwordx4 v[200:201], off
	v_lshl_add_u64 v[200:201], v[224:225], 0, s[14:15]
	s_mov_b32 m0, s52
	s_nop 0
	global_load_lds_dwordx4 v[200:201], off
	v_lshl_add_u64 v[200:201], v[226:227], 0, s[14:15]
	s_mov_b32 m0, s53
	s_nop 0
	global_load_lds_dwordx4 v[200:201], off
	s_waitcnt vmcnt(8)
	s_waitcnt lgkmcnt(0)
	s_barrier
	s_setprio 1
	s_waitcnt lgkmcnt(0)
	v_mfma_f32_16x16x32_bf16 v[60:63], v[112:115], v[160:163], v[60:63]
	v_mfma_f32_16x16x32_bf16 v[56:59], v[136:139], v[160:163], v[56:59]
	v_mfma_f32_16x16x32_bf16 v[44:47], v[112:115], v[168:171], v[44:47]
	v_mfma_f32_16x16x32_bf16 v[40:43], v[136:139], v[168:171], v[40:43]
	v_mfma_f32_16x16x32_bf16 v[28:31], v[112:115], v[206:209], v[28:31]
	v_mfma_f32_16x16x32_bf16 v[24:27], v[136:139], v[206:209], v[24:27]
	v_mfma_f32_16x16x32_bf16 v[12:15], v[112:115], v[214:217], v[12:15]
	v_mfma_f32_16x16x32_bf16 v[8:11], v[136:139], v[214:217], v[8:11]
	v_mfma_f32_16x16x32_bf16 v[60:63], v[116:119], v[164:167], v[60:63]
	v_mfma_f32_16x16x32_bf16 v[56:59], v[140:143], v[164:167], v[56:59]
	v_mfma_f32_16x16x32_bf16 v[44:47], v[116:119], v[172:175], v[44:47]
	v_mfma_f32_16x16x32_bf16 v[40:43], v[140:143], v[172:175], v[40:43]
	v_mfma_f32_16x16x32_bf16 v[28:31], v[116:119], v[210:213], v[28:31]
	v_mfma_f32_16x16x32_bf16 v[24:27], v[140:143], v[210:213], v[24:27]
	v_mfma_f32_16x16x32_bf16 v[12:15], v[116:119], v[218:221], v[12:15]
	v_mfma_f32_16x16x32_bf16 v[8:11], v[140:143], v[218:221], v[8:11]
	s_setprio 0
	s_setprio 1
	v_mfma_f32_16x16x32_bf16 v[52:55], v[144:147], v[160:163], v[52:55]
	v_mfma_f32_16x16x32_bf16 v[48:51], v[152:155], v[160:163], v[48:51]
	v_mfma_f32_16x16x32_bf16 v[36:39], v[144:147], v[168:171], v[36:39]
	v_mfma_f32_16x16x32_bf16 v[32:35], v[152:155], v[168:171], v[32:35]
	v_mfma_f32_16x16x32_bf16 v[20:23], v[144:147], v[206:209], v[20:23]
	v_mfma_f32_16x16x32_bf16 v[16:19], v[152:155], v[206:209], v[16:19]
	v_mfma_f32_16x16x32_bf16 v[4:7], v[144:147], v[214:217], v[4:7]
	v_mfma_f32_16x16x32_bf16 v[0:3], v[152:155], v[214:217], v[0:3]
	v_mfma_f32_16x16x32_bf16 v[52:55], v[148:151], v[164:167], v[52:55]
	v_mfma_f32_16x16x32_bf16 v[48:51], v[156:159], v[164:167], v[48:51]
	v_mfma_f32_16x16x32_bf16 v[36:39], v[148:151], v[172:175], v[36:39]
	v_mfma_f32_16x16x32_bf16 v[32:35], v[156:159], v[172:175], v[32:35]
	v_mfma_f32_16x16x32_bf16 v[20:23], v[148:151], v[210:213], v[20:23]
	v_mfma_f32_16x16x32_bf16 v[16:19], v[156:159], v[210:213], v[16:19]
	v_mfma_f32_16x16x32_bf16 v[4:7], v[148:151], v[218:221], v[4:7]
	v_mfma_f32_16x16x32_bf16 v[0:3], v[156:159], v[218:221], v[0:3]
	s_setprio 0
	s_barrier
	s_add_i32 s82, s82, 2
	s_add_u32 s80, s80, 0x100
	s_addc_u32 s81, s81, 0
	s_cmp_gt_u32 s82, 41
	s_mov_b64 s[20:21], s[22:23]
